# dense attention unit rewritten: staggered wave halves, 4-slot KV LDS rings, single-pass softmax
# speedup vs baseline: 1.0184x; 1.0184x over previous
; __device__ __forceinline__ int TID() { int t = threadIdx.x; asm volatile("" : "+v"(t)); return t; }
; __device__ __forceinline__ int v_rd_base(int lane) { return ((lane & 3) << 3) | (((lane >> 2) & 3) << 6) | (((lane >> 4) & 1) << 5) | (((lane >> 5) & 1) << 8); }
; #define SWAIT() do { if constexpr (SDEPTH == 2) asm volatile("s_waitcnt vmcnt(4)" ::: "memory"); else asm volatile("s_waitcnt vmcnt(0)" ::: "memory"); } while (0)
; #define ROW0(t) tile_row0<MODE>(u, (t))
; template <int MODE, int SDEPTH>
; __device__ __forceinline__ void attn_unit(const UnitP& u, char* lds) {
;   const int tid = TID(), wid = tid >> 6, lane = tid & 63, r32 = lane & 31, hi = lane >> 5;
;   bf16_t* V_lds = (bf16_t*)lds; bf16_t* K_lds = (bf16_t*)(lds + 2 * SHM_V);
;   float* ws = (float*)(lds + 2 * SHM_V + 2 * SHM_K) + wid * 64; float* li_l = ws; float* al_l = ws + 32;
;   const float* biasL = (const float*)(lds + BIAS_OFF);
;   const bf16_t* __restrict__ Kh = u.K; const bf16_t* __restrict__ Vh = u.V; const int LDK = u.ldk;
;   float m_reg = -1e30f, l_reg = 0; f32x16 o[4] = {}; bf16x8 qr[8];
;   const bf16_t* Qw = u.Q + (long)(wid * QBLK + r32) * u.ldq + hi * 8;
; #pragma unroll
;   for (int d0 = 0; d0 < 8; ++d0) qr[d0] = *reinterpret_cast<const bf16x8*>(Qw + d0 * 16);
;   const int vb0 = (int)(uintptr_t)V_lds + v_rd_base(lane);
;   struct { bf16x8 vs0, vs1, ks0, ks1; } sr_[SDEPTH];
;     ...
;   f32x16 pA0, pA1, pB0, pB1; float mnA, mnB, alA, alB; bf16x8 pa0, pa1, pa2, pa3; const int NT = u.NT;
;   constexpr int SE = 0, SO = SDEPTH - 1;
;   SLOAD(SE, ROW0(0)); asm volatile("s_waitcnt vmcnt(0)" ::: "memory"); SWRITE(0, SE); __syncthreads();
;   qkt(pA0, pA1, K_lds, qr, r32, hi); mask_tile<MODE>(pA0, pA1, u, 0, wid, r32, hi, biasL); partialSM(pA0, pA1, m_reg, mnA, alA);
;   SLOAD(SO, ROW0(1)); if constexpr (SDEPTH == 2) { if (2 < NT) SLOAD(SE, ROW0(2)); }
;   SWAIT(); SWRITE(1, SO); __syncthreads();
.LBB0_528:
	s_andn2_b64 vcc, exec, s[8:9]
	s_mov_b64 s[8:9], -1
	s_cbranch_vccnz .LBB0_524
	s_lshl_b32 s2, s12, 8
	s_and_b32 s29, s2, 0x1f00
	s_and_b32 s13, s12, 0xffffff80
	s_mul_i32 s2, s29, 0x1800
	s_add_u32 s10, s19, s2
	s_addc_u32 s11, s20, 0
	s_lshl_b32 s2, s12, 2
	s_and_b32 s2, s2, 0xffffff80
	s_ashr_i32 s3, s2, 31
	s_lshl_b64 s[8:9], s[2:3], 1
	s_add_u32 s2, s10, s8
	s_addc_u32 s3, s11, s9
	s_add_i32 s10, s13, 0x800
	s_ashr_i32 s11, s10, 31
	s_lshl_b64 s[10:11], s[10:11], 1
	s_add_u32 s14, s19, s10
	s_addc_u32 s15, s20, s11
	s_add_i32 s12, s13, 0xa00
	s_ashr_i32 s13, s12, 31
	s_lshl_b64 s[12:13], s[12:13], 1
	v_mov_b32_e32 v48, v216
	s_add_u32 s16, s19, s12
	s_addc_u32 s17, s20, s13
	v_ashrrev_i32_e32 v195, 6, v48
	v_and_b32_e32 v193, 31, v48
	v_and_b32_e32 v0, 0x3fffffc0, v48
	s_add_i32 s34, 0, 0x10000
	v_lshlrev_b32_e32 v98, 5, v195
	v_bfe_u32 v194, v48, 5, 1
	v_lshl_add_u32 v99, v0, 2, s34
	v_or_b32_e32 v2, v98, v193
	v_mov_b64_e32 v[0:1], s[2:3]
	s_movk_i32 s36, 0x1800
	v_mad_i64_i32 v[0:1], s[2:3], v2, s36, v[0:1]
	v_lshlrev_b32_e32 v96, 4, v194
	v_and_b32_e32 v101, 63, v48
	v_lshl_add_u64 v[0:1], v[0:1], 0, v[96:97]
	v_lshlrev_b32_e32 v192, 4, v48
	global_load_dwordx4 v[130:133], v[0:1], off
	global_load_dwordx4 v[126:129], v[0:1], off offset:32
	global_load_dwordx4 v[122:125], v[0:1], off offset:64
	global_load_dwordx4 v[118:121], v[0:1], off offset:96
	global_load_dwordx4 v[114:117], v[0:1], off offset:128
	global_load_dwordx4 v[110:113], v[0:1], off offset:160
	global_load_dwordx4 v[106:109], v[0:1], off offset:192
	global_load_dwordx4 v[102:105], v[0:1], off offset:224
	v_lshlrev_b32_e32 v99, 8, v195
	v_add_u32_e32 v99, 0x22000, v99
	v_lshl_add_u32 v199, v193, 2, v99
	v_cmp_gt_u32_e64 s[40:41], 32, v101
	v_lshlrev_b32_e32 v0, 3, v101
	v_and_b32_e32 v1, 0xc0, v192
	v_lshlrev_b32_e32 v2, 1, v48
	v_and_or_b32 v1, v0, 24, v1
	v_and_b32_e32 v2, 32, v2
	v_and_b32_e32 v0, 0x100, v0
	v_or3_b32 v196, v1, v2, v0
	v_ashrrev_i32_e32 v50, 4, v48
	v_lshlrev_b32_e32 v16, 3, v48
	v_and_b32_e32 v51, 0x78, v16
	v_and_b32_e32 v3, 15, v48
	v_lshlrev_b32_e32 v3, 4, v3
	v_mov_b32_e32 v5, 0
	s_movk_i32 s2, 0x1800
	v_mad_u32_u24 v4, v50, s2, v3
	v_lshl_add_u64 v[188:189], s[16:17], 0, v[4:5]
	v_lshl_add_u64 v[184:185], s[14:15], 0, v[4:5]
	s_mov_b64 s[2:3], 0x30000
	v_lshl_add_u64 v[190:191], v[188:189], 0, s[2:3]
	v_lshl_add_u64 v[186:187], v[184:185], 0, s[2:3]
	s_mov_b64 s[2:3], 0x60000
	global_load_dwordx4 v[134:137], v[188:189], off
	global_load_dwordx4 v[138:141], v[190:191], off
	global_load_dwordx4 v[142:145], v[184:185], off
	global_load_dwordx4 v[146:149], v[186:187], off
	v_lshl_add_u64 v[184:185], v[184:185], 0, s[2:3]
	v_lshl_add_u64 v[186:187], v[186:187], 0, s[2:3]
	v_lshl_add_u64 v[188:189], v[188:189], 0, s[2:3]
	v_lshl_add_u64 v[190:191], v[190:191], 0, s[2:3]
	global_load_dwordx4 v[150:153], v[188:189], off
	global_load_dwordx4 v[154:157], v[190:191], off
	global_load_dwordx4 v[158:161], v[184:185], off
	global_load_dwordx4 v[162:165], v[186:187], off
	v_lshl_add_u64 v[184:185], v[184:185], 0, s[2:3]
	v_lshl_add_u64 v[186:187], v[186:187], 0, s[2:3]
	v_lshl_add_u64 v[188:189], v[188:189], 0, s[2:3]
	v_lshl_add_u64 v[190:191], v[190:191], 0, s[2:3]
	v_and_b32_e32 v18, 0xfffff0, v50
	v_lshlrev_b32_e32 v19, 1, v50
	v_and_or_b32 v18, v19, 8, v18
	v_lshrrev_b32_e32 v19, 1, v50
	v_lshrrev_b32_e32 v18, 1, v18
	v_bfe_u32 v16, v16, 5, 2
	v_and_b32_e32 v20, 3, v50
	v_or_b32_e32 v18, v18, v16
	v_and_or_b32 v19, v19, 4, v20
	v_lshlrev_b32_e32 v20, 1, v51
	v_lshlrev_b32_e32 v18, 9, v18
	v_lshlrev_b32_e32 v19, 6, v19
	v_and_b32_e32 v21, 48, v20
	v_or3_b32 v197, v18, v19, v21
	v_lshlrev_b32_e32 v4, 8, v50
	v_and_b32_e32 v5, 0x70, v48
	v_bitop3_b32 v4, v20, v4, v5 bitop3:0xde
	v_add_u32_e32 v200, 0x10000, v4
	v_lshlrev_b32_e32 v60, 8, v193
	v_and_b32_e32 v61, 0x70, v192
	v_bitop3_b32 v52, v96, v60, v61 bitop3:0xde
	v_add_u32_e32 v204, 0x10000, v52
	v_or_b32_e32 v52, 32, v96
	v_bitop3_b32 v52, v52, v60, v61 bitop3:0xde
	v_add_u32_e32 v205, 0x10000, v52
	v_or_b32_e32 v52, 64, v96
	v_bitop3_b32 v52, v52, v60, v61 bitop3:0xde
	v_add_u32_e32 v206, 0x10000, v52
	v_or_b32_e32 v52, 96, v96
	v_bitop3_b32 v52, v52, v60, v61 bitop3:0xde
	v_add_u32_e32 v207, 0x10000, v52
	v_or_b32_e32 v52, 128, v96
	v_bitop3_b32 v52, v52, v60, v61 bitop3:0xde
	v_add_u32_e32 v208, 0x10000, v52
	v_or_b32_e32 v52, 160, v96
	v_bitop3_b32 v52, v52, v60, v61 bitop3:0xde
	v_add_u32_e32 v209, 0x10000, v52
	v_or_b32_e32 v52, 192, v96
	v_bitop3_b32 v52, v52, v60, v61 bitop3:0xde
	v_add_u32_e32 v210, 0x10000, v52
	v_or_b32_e32 v52, 224, v96
	v_bitop3_b32 v52, v52, v60, v61 bitop3:0xde
	v_add_u32_e32 v211, 0x10000, v52
	v_mov_b32_e32 v174, v224
	v_mov_b32_e32 v175, 0
	s_mov_b32 s100, 0
	v_readfirstlane_b32 s101, v195
	s_waitcnt vmcnt(4)
	ds_write_b128 v197, v[134:137] offset:0
	ds_write_b128 v197, v[138:141] offset:8192
	ds_write_b128 v200, v[142:145] offset:0
	ds_write_b128 v200, v[146:149] offset:8192
	s_waitcnt vmcnt(0)
	ds_write_b128 v197, v[150:153] offset:16384
	ds_write_b128 v197, v[154:157] offset:24576
	ds_write_b128 v200, v[158:161] offset:16384
	ds_write_b128 v200, v[162:165] offset:24576
	s_nop 1
	global_load_dwordx4 v[134:137], v[188:189], off
	global_load_dwordx4 v[138:141], v[190:191], off
	global_load_dwordx4 v[142:145], v[184:185], off
	global_load_dwordx4 v[146:149], v[186:187], off
	v_lshl_add_u64 v[184:185], v[184:185], 0, s[2:3]
	v_lshl_add_u64 v[186:187], v[186:187], 0, s[2:3]
	v_lshl_add_u64 v[188:189], v[188:189], 0, s[2:3]
	v_lshl_add_u64 v[190:191], v[190:191], 0, s[2:3]
	v_mov_b32_e32 v0, 0
	v_mov_b32_e32 v1, 0
	v_mov_b32_e32 v2, 0
	v_mov_b32_e32 v3, 0
	v_mov_b32_e32 v4, 0
	v_mov_b32_e32 v5, 0
	v_mov_b32_e32 v6, 0
	v_mov_b32_e32 v7, 0
	v_mov_b32_e32 v8, 0
	v_mov_b32_e32 v9, 0
	v_mov_b32_e32 v10, 0
	v_mov_b32_e32 v11, 0
	v_mov_b32_e32 v12, 0
	v_mov_b32_e32 v13, 0
	v_mov_b32_e32 v14, 0
	v_mov_b32_e32 v15, 0
	v_mov_b32_e32 v48, 0
	v_mov_b32_e32 v49, 0
	v_mov_b32_e32 v50, 0
	v_mov_b32_e32 v51, 0
	v_mov_b32_e32 v52, 0
	v_mov_b32_e32 v53, 0
	v_mov_b32_e32 v54, 0
	v_mov_b32_e32 v55, 0
	v_mov_b32_e32 v56, 0
	v_mov_b32_e32 v57, 0
	v_mov_b32_e32 v58, 0
	v_mov_b32_e32 v59, 0
	v_mov_b32_e32 v60, 0
	v_mov_b32_e32 v61, 0
	v_mov_b32_e32 v62, 0
	v_mov_b32_e32 v63, 0
	v_mov_b32_e32 v32, 0
	v_mov_b32_e32 v33, 0
	v_mov_b32_e32 v34, 0
	v_mov_b32_e32 v35, 0
	v_mov_b32_e32 v36, 0
	v_mov_b32_e32 v37, 0
	v_mov_b32_e32 v38, 0
	v_mov_b32_e32 v39, 0
	v_mov_b32_e32 v40, 0
	v_mov_b32_e32 v41, 0
	v_mov_b32_e32 v42, 0
	v_mov_b32_e32 v43, 0
	v_mov_b32_e32 v44, 0
	v_mov_b32_e32 v45, 0
	v_mov_b32_e32 v46, 0
	v_mov_b32_e32 v47, 0
	v_mov_b32_e32 v16, 0
	v_mov_b32_e32 v17, 0
	v_mov_b32_e32 v18, 0
	v_mov_b32_e32 v19, 0
	v_mov_b32_e32 v20, 0
	v_mov_b32_e32 v21, 0
	v_mov_b32_e32 v22, 0
	v_mov_b32_e32 v23, 0
	v_mov_b32_e32 v24, 0
	v_mov_b32_e32 v25, 0
	v_mov_b32_e32 v26, 0
	v_mov_b32_e32 v27, 0
	v_mov_b32_e32 v28, 0
	v_mov_b32_e32 v29, 0
	v_mov_b32_e32 v30, 0
	v_mov_b32_e32 v31, 0
	s_waitcnt lgkmcnt(0)
	s_barrier
; #define SBAR() __builtin_amdgcn_sched_barrier(0)
; __device__ __forceinline__ void qkt(f32x16& p0, f32x16& p1, const bf16_t* Ks, const bf16x8* qr, int r32, int hi) {
;   p0 = f32x16{}; p1 = f32x16{};
; #pragma unroll
;   for (int d0 = 0; d0 < 8; ++d0) { int cb = (d0 * 16 + hi * 8) * 2;
;     bf16x8 b0 = *reinterpret_cast<const bf16x8*>((const char*)Ks + KSWZ(r32, cb));
;     bf16x8 b1 = *reinterpret_cast<const bf16x8*>((const char*)Ks + KSWZ(32 + r32, cb));
;     p0 = __builtin_amdgcn_mfma_f32_32x32x16_bf16(b0, qr[d0], p0, 0, 0, 0);
;     p1 = __builtin_amdgcn_mfma_f32_32x32x16_bf16(b1, qr[d0], p1, 0, 0, 0); }
; }
; __device__ __forceinline__ int v_st(int k, int c) { const int kk = (k & ~0xC) | ((k & 4) << 1) | ((k & 8) >> 1); return ((kk >> 3) * 4 + (c >> 5)) * 512 + ((kk & 7) * 32 + (c & 31)) * 2; }
; __device__ __forceinline__ int v_rd_base(int lane) { return ((lane & 3) << 3) | (((lane >> 2) & 3) << 6) | (((lane >> 4) & 1) << 5) | (((lane >> 5) & 1) << 8); }
; template <int OFF> __device__ __forceinline__ s16x4 tr_read(int vb) {
;   s16x4 r; asm volatile("ds_read_b64_tr_b16 %0, %1 offset:%2" : "=&v"(r) : "v"(vb), "i"(OFF) : "memory"); return r;
; }
; template <int D0> __device__ __forceinline__ void pv_one(f32x16& od, int vb, bf16x8 pa0, bf16x8 pa1, bf16x8 pa2, bf16x8 pa3) {
;   const s16x4 l0 = tr_read<v_rd_off(D0, 0, 0)>(vb), h0 = tr_read<v_rd_off(D0, 0, 1)>(vb), l1 = tr_read<v_rd_off(D0, 1, 0)>(vb), h1 = tr_read<v_rd_off(D0, 1, 1)>(vb);
;   const s16x4 l2 = tr_read<v_rd_off(D0, 2, 0)>(vb), h2 = tr_read<v_rd_off(D0, 2, 1)>(vb), l3 = tr_read<v_rd_off(D0, 3, 0)>(vb), h3 = tr_read<v_rd_off(D0, 3, 1)>(vb);
;   asm volatile("s_waitcnt lgkmcnt(0)" ::: "memory"); SBAR();
;     ...
;   od = __builtin_amdgcn_mfma_f32_32x32x16_bf16(pa0, PK(l0, h0), od, 0, 0, 0);
;   od = __builtin_amdgcn_mfma_f32_32x32x16_bf16(pa1, PK(l1, h1), od, 0, 0, 0);
;   od = __builtin_amdgcn_mfma_f32_32x32x16_bf16(pa2, PK(l2, h2), od, 0, 0, 0);
;   od = __builtin_amdgcn_mfma_f32_32x32x16_bf16(pa3, PK(l3, h3), od, 0, 0, 0);
;     ...
; }
; __device__ __forceinline__ void pv_d0(f32x16* o, int vb, bf16x8 pa0, bf16x8 pa1, bf16x8 pa2, bf16x8 pa3) {
;   pv_one<0>(o[0], vb, pa0, pa1, pa2, pa3); pv_one<1>(o[1], vb, pa0, pa1, pa2, pa3); pv_one<2>(o[2], vb, pa0, pa1, pa2, pa3); pv_one<3>(o[3], vb, pa0, pa1, pa2, pa3);
	ds_read_b128 v[150:153], v204 offset:0
	ds_read_b128 v[154:157], v204 offset:8192
	ds_read_b128 v[158:161], v205 offset:0
	ds_read_b128 v[162:165], v205 offset:8192
	ds_read_b128 v[228:231], v206 offset:0
	ds_read_b128 v[232:235], v206 offset:8192
	ds_read_b128 v[236:239], v207 offset:0
	ds_read_b128 v[240:243], v207 offset:8192
	s_cmp_lt_u32 s101, 4
	s_cbranch_scc1 .Lda_lead
	s_barrier
.Lda_lead:
	s_waitcnt lgkmcnt(6)
	v_mfma_f32_32x32x16_bf16 v[80:95], v[150:153], v[130:133], 0
	v_mfma_f32_32x32x16_bf16 v[64:79], v[154:157], v[130:133], 0
	ds_read_b128 v[150:153], v208 offset:0
	ds_read_b128 v[154:157], v208 offset:8192
	s_waitcnt lgkmcnt(6)
	v_mfma_f32_32x32x16_bf16 v[80:95], v[158:161], v[126:129], v[80:95]
	v_mfma_f32_32x32x16_bf16 v[64:79], v[162:165], v[126:129], v[64:79]
	ds_read_b128 v[158:161], v209 offset:0
	ds_read_b128 v[162:165], v209 offset:8192
	s_waitcnt lgkmcnt(6)
	v_mfma_f32_32x32x16_bf16 v[80:95], v[228:231], v[122:125], v[80:95]
	v_mfma_f32_32x32x16_bf16 v[64:79], v[232:235], v[122:125], v[64:79]
	ds_read_b128 v[228:231], v210 offset:0
	ds_read_b128 v[232:235], v210 offset:8192
	s_waitcnt lgkmcnt(6)
	v_mfma_f32_32x32x16_bf16 v[80:95], v[236:239], v[118:121], v[80:95]
	v_mfma_f32_32x32x16_bf16 v[64:79], v[240:243], v[118:121], v[64:79]
	ds_read_b128 v[236:239], v211 offset:0
	ds_read_b128 v[240:243], v211 offset:8192
	s_waitcnt lgkmcnt(6)
	v_mfma_f32_32x32x16_bf16 v[80:95], v[150:153], v[114:117], v[80:95]
	v_mfma_f32_32x32x16_bf16 v[64:79], v[154:157], v[114:117], v[64:79]
	s_waitcnt lgkmcnt(4)
	v_mfma_f32_32x32x16_bf16 v[80:95], v[158:161], v[110:113], v[80:95]
	v_mfma_f32_32x32x16_bf16 v[64:79], v[162:165], v[110:113], v[64:79]
	s_waitcnt lgkmcnt(2)
	v_mfma_f32_32x32x16_bf16 v[80:95], v[228:231], v[106:109], v[80:95]
	v_mfma_f32_32x32x16_bf16 v[64:79], v[232:235], v[106:109], v[64:79]
	s_waitcnt lgkmcnt(0)
	v_mfma_f32_32x32x16_bf16 v[80:95], v[236:239], v[102:105], v[80:95]
	v_mfma_f32_32x32x16_bf16 v[64:79], v[240:243], v[102:105], v[64:79]
	s_nop 12
	s_branch .Lda_y0
.Lda_loop:
	s_waitcnt lgkmcnt(6)
	v_mfma_f32_32x32x16_bf16 v[80:95], v[150:153], v[130:133], 0
	v_mfma_f32_32x32x16_bf16 v[64:79], v[154:157], v[130:133], 0
	ds_read_b128 v[150:153], v208 offset:0
	ds_read_b128 v[154:157], v208 offset:8192
	s_waitcnt lgkmcnt(6)
	v_mfma_f32_32x32x16_bf16 v[80:95], v[158:161], v[126:129], v[80:95]
	v_mfma_f32_32x32x16_bf16 v[64:79], v[162:165], v[126:129], v[64:79]
	ds_read_b128 v[158:161], v209 offset:0
	ds_read_b128 v[162:165], v209 offset:8192
	s_waitcnt lgkmcnt(6)
	v_mfma_f32_32x32x16_bf16 v[80:95], v[228:231], v[122:125], v[80:95]
	v_mfma_f32_32x32x16_bf16 v[64:79], v[232:235], v[122:125], v[64:79]
	ds_read_b128 v[228:231], v210 offset:0
	ds_read_b128 v[232:235], v210 offset:8192
	s_waitcnt lgkmcnt(6)
	v_mfma_f32_32x32x16_bf16 v[80:95], v[236:239], v[118:121], v[80:95]
	v_mfma_f32_32x32x16_bf16 v[64:79], v[240:243], v[118:121], v[64:79]
	ds_read_b128 v[236:239], v211 offset:0
	ds_read_b128 v[240:243], v211 offset:8192
	s_waitcnt lgkmcnt(6)
	v_mfma_f32_32x32x16_bf16 v[80:95], v[150:153], v[114:117], v[80:95]
	v_mfma_f32_32x32x16_bf16 v[64:79], v[154:157], v[114:117], v[64:79]
	ds_read_b64_tr_b16 v[150:151], v196 offset:49152
	ds_read_b64_tr_b16 v[152:153], v196 offset:51200
	ds_read_b64_tr_b16 v[154:155], v196 offset:53248
	ds_read_b64_tr_b16 v[156:157], v196 offset:55296
	s_waitcnt lgkmcnt(8)
	v_mfma_f32_32x32x16_bf16 v[80:95], v[158:161], v[110:113], v[80:95]
	v_mfma_f32_32x32x16_bf16 v[64:79], v[162:165], v[110:113], v[64:79]
	ds_read_b64_tr_b16 v[158:159], v196 offset:57344
	ds_read_b64_tr_b16 v[160:161], v196 offset:59392
	ds_read_b64_tr_b16 v[162:163], v196 offset:61440
	ds_read_b64_tr_b16 v[164:165], v196 offset:63488
	s_waitcnt lgkmcnt(10)
	v_mfma_f32_32x32x16_bf16 v[80:95], v[228:231], v[106:109], v[80:95]
	v_mfma_f32_32x32x16_bf16 v[64:79], v[232:235], v[106:109], v[64:79]
	ds_read_b64_tr_b16 v[228:229], v196 offset:49664
	ds_read_b64_tr_b16 v[230:231], v196 offset:51712
	ds_read_b64_tr_b16 v[232:233], v196 offset:53760
	ds_read_b64_tr_b16 v[234:235], v196 offset:55808
	s_waitcnt lgkmcnt(12)
	v_mfma_f32_32x32x16_bf16 v[80:95], v[236:239], v[102:105], v[80:95]
	v_mfma_f32_32x32x16_bf16 v[64:79], v[240:243], v[102:105], v[64:79]
	ds_read_b64_tr_b16 v[236:237], v196 offset:57856
	ds_read_b64_tr_b16 v[238:239], v196 offset:59904
	s_waitcnt lgkmcnt(12)
	v_mfma_f32_32x32x16_bf16 v[0:15], v[166:169], v[150:153], v[0:15]
	ds_read_b64_tr_b16 v[240:241], v196 offset:61952
	ds_read_b64_tr_b16 v[242:243], v196 offset:64000
	s_waitcnt lgkmcnt(12)
	v_mfma_f32_32x32x16_bf16 v[0:15], v[170:173], v[154:157], v[0:15]
	ds_read_b64_tr_b16 v[150:151], v196 offset:50176
	ds_read_b64_tr_b16 v[152:153], v196 offset:52224
	s_waitcnt lgkmcnt(12)
	v_mfma_f32_32x32x16_bf16 v[0:15], v[176:179], v[158:161], v[0:15]
	ds_read_b64_tr_b16 v[154:155], v196 offset:54272
	ds_read_b64_tr_b16 v[156:157], v196 offset:56320
	s_waitcnt lgkmcnt(12)
	v_mfma_f32_32x32x16_bf16 v[0:15], v[180:183], v[162:165], v[0:15]
	ds_read_b64_tr_b16 v[158:159], v196 offset:58368
	ds_read_b64_tr_b16 v[160:161], v196 offset:60416
	s_waitcnt lgkmcnt(12)
	v_mfma_f32_32x32x16_bf16 v[48:63], v[166:169], v[228:231], v[48:63]
	ds_read_b64_tr_b16 v[162:163], v196 offset:62464
	ds_read_b64_tr_b16 v[164:165], v196 offset:64512
	s_waitcnt lgkmcnt(12)
	v_mfma_f32_32x32x16_bf16 v[48:63], v[170:173], v[232:235], v[48:63]
	ds_read_b64_tr_b16 v[228:229], v196 offset:50688
	ds_read_b64_tr_b16 v[230:231], v196 offset:52736
	s_waitcnt lgkmcnt(12)
	v_mfma_f32_32x32x16_bf16 v[48:63], v[176:179], v[236:239], v[48:63]
	ds_read_b64_tr_b16 v[232:233], v196 offset:54784
	ds_read_b64_tr_b16 v[234:235], v196 offset:56832
	s_waitcnt lgkmcnt(12)
	v_mfma_f32_32x32x16_bf16 v[48:63], v[180:183], v[240:243], v[48:63]
	ds_read_b64_tr_b16 v[236:237], v196 offset:58880
	ds_read_b64_tr_b16 v[238:239], v196 offset:60928
	s_waitcnt lgkmcnt(12)
	v_mfma_f32_32x32x16_bf16 v[32:47], v[166:169], v[150:153], v[32:47]
	ds_read_b64_tr_b16 v[240:241], v196 offset:62976
	ds_read_b64_tr_b16 v[242:243], v196 offset:65024
	s_waitcnt lgkmcnt(12)
	v_mfma_f32_32x32x16_bf16 v[32:47], v[170:173], v[154:157], v[32:47]
	s_waitcnt lgkmcnt(10)
	v_mfma_f32_32x32x16_bf16 v[32:47], v[176:179], v[158:161], v[32:47]
	s_waitcnt lgkmcnt(8)
	v_mfma_f32_32x32x16_bf16 v[32:47], v[180:183], v[162:165], v[32:47]
	s_waitcnt lgkmcnt(6)
	v_mfma_f32_32x32x16_bf16 v[16:31], v[166:169], v[228:231], v[16:31]
	s_waitcnt lgkmcnt(4)
	v_mfma_f32_32x32x16_bf16 v[16:31], v[170:173], v[232:235], v[16:31]
	s_waitcnt lgkmcnt(2)
	v_mfma_f32_32x32x16_bf16 v[16:31], v[176:179], v[236:239], v[16:31]
	s_waitcnt lgkmcnt(0)
	v_mfma_f32_32x32x16_bf16 v[16:31], v[180:183], v[240:243], v[16:31]
; __device__ __forceinline__ void partialSM(f32x16& p0, f32x16& p1, float& m_reg, float& mn, float& alpha) {
;   constexpr float C = SCALE * 1.4426950408889634f;
;   float pmax = p0[0];
; #pragma unroll
;   for (int r = 1; r < 16; ++r) pmax = fmaxf(pmax, p0[r]);
; #pragma unroll
;   for (int r = 0; r < 16; ++r) pmax = fmaxf(pmax, p1[r]);
;   { auto rr = __builtin_amdgcn_permlane32_swap(__float_as_uint(pmax), __float_as_uint(pmax), false, false);
;     pmax = fmaxf(__uint_as_float(rr[0]), __uint_as_float(rr[1])); }
;   if (__builtin_expect(__all(pmax - m_reg <= THR / SCALE), 1)) { mn = m_reg; alpha = 1.f; }
;   else { mn = fmaxf(m_reg, pmax); alpha = __builtin_amdgcn_exp2f((m_reg - mn) * C); m_reg = mn; }
;   float mnC = -mn * C;
; #pragma unroll
;   for (int r = 0; r < 16; ++r) p0[r] = fmaf(p0[r], C, mnC);
; #pragma unroll
;   for (int r = 0; r < 16; ++r) p1[r] = fmaf(p1[r], C, mnC);
; #pragma unroll
;   for (int r = 0; r < 16; ++r) p0[r] = __builtin_amdgcn_exp2f(p0[r]);
; }
; __device__ __forceinline__ void finishSM(f32x16& p0, f32x16& p1, float alpha, float& l_reg, bf16x8& pa0, bf16x8& pa1, bf16x8& pa2, bf16x8& pa3) {
; #pragma unroll
;   for (int r = 0; r < 16; ++r) p1[r] = __builtin_amdgcn_exp2f(p1[r]);
;   float ps = 0;
; #pragma unroll
;   for (int r = 0; r < 16; ++r) ps += p0[r];
; #pragma unroll
;   for (int r = 0; r < 16; ++r) ps += p1[r];
;   { auto rr = __builtin_amdgcn_permlane32_swap(__float_as_uint(ps), __float_as_uint(ps), false, false);
;     ps = __uint_as_float(rr[0]) + __uint_as_float(rr[1]); }
;   l_reg = l_reg * alpha + ps;
;     ...
;   PK4(p0, 0, pa0); PK4(p0, 8, pa1); PK4(p1, 0, pa2); PK4(p1, 8, pa3);
;     ...
; }
.Lda_y0:
	s_barrier
	v_max3_f32 v201, v80, v81, v82
	v_max3_f32 v202, v64, v65, v66
	v_max3_f32 v201, v201, v83, v84
	v_max3_f32 v202, v202, v67, v68
	v_max3_f32 v201, v201, v85, v86
	v_max3_f32 v202, v202, v69, v70
	v_max3_f32 v201, v201, v87, v88
	v_max3_f32 v202, v202, v71, v72
	v_max3_f32 v201, v201, v89, v90
	v_max3_f32 v202, v202, v73, v74
	v_max3_f32 v201, v201, v91, v92
	v_max3_f32 v202, v202, v75, v76
	v_max3_f32 v201, v201, v93, v94
	v_max3_f32 v202, v202, v77, v78
	v_max3_f32 v201, v201, v95, v79
	v_max_f32_e32 v201, v201, v202
	v_mov_b32_e32 v202, v201
	s_nop 1
	v_permlane32_swap_b32_e32 v201, v202
	s_nop 0
	v_max_f32_e32 v212, v201, v202
	v_sub_f32_e32 v201, v212, v174
	v_cmp_ge_f32_e32 vcc, s86, v201
	v_max_f32_e32 v202, v174, v212
	v_sub_f32_e32 v215, v174, v202
	v_mul_f32_e32 v215, s92, v215
	s_nop 1
	s_cmp_eq_u64 vcc, exec
	s_cselect_b64 s[42:43], -1, 0
	v_exp_f32_e32 v213, v215
	s_nop 0
	v_cndmask_b32_e64 v174, v202, v174, s[42:43]
	v_cndmask_b32_e64 v213, v213, 1.0, s[42:43]
	v_mul_f32_e32 v214, 0xbe0293ee, v174
	s_nop 0
	v_cmp_gt_f32_e32 vcc, 1.0, v213
	v_fma_f32 v80, v80, s92, v214
	v_fma_f32 v81, v81, s92, v214
	v_fma_f32 v82, v82, s92, v214
	v_fma_f32 v83, v83, s92, v214
	v_fma_f32 v84, v84, s92, v214
	v_fma_f32 v85, v85, s92, v214
	v_fma_f32 v86, v86, s92, v214
	v_fma_f32 v87, v87, s92, v214
	v_fma_f32 v88, v88, s92, v214
	v_fma_f32 v89, v89, s92, v214
	v_fma_f32 v90, v90, s92, v214
	v_fma_f32 v91, v91, s92, v214
	v_fma_f32 v92, v92, s92, v214
	v_fma_f32 v93, v93, s92, v214
	v_fma_f32 v94, v94, s92, v214
	v_fma_f32 v95, v95, s92, v214
	v_fma_f32 v64, v64, s92, v214
	v_fma_f32 v65, v65, s92, v214
	v_fma_f32 v66, v66, s92, v214
	v_fma_f32 v67, v67, s92, v214
	v_fma_f32 v68, v68, s92, v214
	v_fma_f32 v69, v69, s92, v214
	v_fma_f32 v70, v70, s92, v214
	v_fma_f32 v71, v71, s92, v214
	v_fma_f32 v72, v72, s92, v214
	v_fma_f32 v73, v73, s92, v214
	v_fma_f32 v74, v74, s92, v214
	v_fma_f32 v75, v75, s92, v214
	v_fma_f32 v76, v76, s92, v214
	v_fma_f32 v77, v77, s92, v214
	v_fma_f32 v78, v78, s92, v214
	v_fma_f32 v79, v79, s92, v214
	s_cbranch_vccz .Lda_noresc_0
	s_and_saveexec_b64 s[34:35], s[40:41]
	ds_write_b32 v199, v213 offset:128
	s_or_b64 exec, exec, s[34:35]
	s_waitcnt lgkmcnt(0)
	v_add_u32_e32 v215, v99, v96
	ds_read_b128 v[228:231], v215 offset:128
	ds_read_b128 v[232:235], v215 offset:160
	ds_read_b128 v[236:239], v215 offset:192
	ds_read_b128 v[240:243], v215 offset:224
	s_waitcnt lgkmcnt(0)
	v_pk_mul_f32 v[0:1], v[0:1], v[228:229]
	v_pk_mul_f32 v[2:3], v[2:3], v[230:231]
	v_pk_mul_f32 v[4:5], v[4:5], v[232:233]
	v_pk_mul_f32 v[6:7], v[6:7], v[234:235]
	v_pk_mul_f32 v[8:9], v[8:9], v[236:237]
	v_pk_mul_f32 v[10:11], v[10:11], v[238:239]
	v_pk_mul_f32 v[12:13], v[12:13], v[240:241]
	v_pk_mul_f32 v[14:15], v[14:15], v[242:243]
	v_pk_mul_f32 v[48:49], v[48:49], v[228:229]
	v_pk_mul_f32 v[50:51], v[50:51], v[230:231]
	v_pk_mul_f32 v[52:53], v[52:53], v[232:233]
	v_pk_mul_f32 v[54:55], v[54:55], v[234:235]
	v_pk_mul_f32 v[56:57], v[56:57], v[236:237]
	v_pk_mul_f32 v[58:59], v[58:59], v[238:239]
	v_pk_mul_f32 v[60:61], v[60:61], v[240:241]
	v_pk_mul_f32 v[62:63], v[62:63], v[242:243]
	v_pk_mul_f32 v[32:33], v[32:33], v[228:229]
	v_pk_mul_f32 v[34:35], v[34:35], v[230:231]
	v_pk_mul_f32 v[36:37], v[36:37], v[232:233]
	v_pk_mul_f32 v[38:39], v[38:39], v[234:235]
	v_pk_mul_f32 v[40:41], v[40:41], v[236:237]
	v_pk_mul_f32 v[42:43], v[42:43], v[238:239]
	v_pk_mul_f32 v[44:45], v[44:45], v[240:241]
	v_pk_mul_f32 v[46:47], v[46:47], v[242:243]
	v_pk_mul_f32 v[16:17], v[16:17], v[228:229]
	v_pk_mul_f32 v[18:19], v[18:19], v[230:231]
	v_pk_mul_f32 v[20:21], v[20:21], v[232:233]
	v_pk_mul_f32 v[22:23], v[22:23], v[234:235]
	v_pk_mul_f32 v[24:25], v[24:25], v[236:237]
	v_pk_mul_f32 v[26:27], v[26:27], v[238:239]
	v_pk_mul_f32 v[28:29], v[28:29], v[240:241]
	v_pk_mul_f32 v[30:31], v[30:31], v[242:243]
.Lda_noresc_0:
	v_exp_f32_e32 v80, v80
	v_exp_f32_e32 v81, v81
	v_exp_f32_e32 v82, v82
	v_exp_f32_e32 v83, v83
	v_exp_f32_e32 v84, v84
	v_exp_f32_e32 v85, v85
	v_exp_f32_e32 v86, v86
	v_exp_f32_e32 v87, v87
	v_exp_f32_e32 v88, v88
	v_exp_f32_e32 v89, v89
	v_exp_f32_e32 v90, v90
	v_exp_f32_e32 v91, v91
	v_exp_f32_e32 v92, v92
	v_exp_f32_e32 v93, v93
	v_exp_f32_e32 v94, v94
	v_exp_f32_e32 v95, v95
	v_exp_f32_e32 v64, v64
	v_exp_f32_e32 v65, v65
	v_exp_f32_e32 v66, v66
	v_exp_f32_e32 v67, v67
	v_exp_f32_e32 v68, v68
	v_exp_f32_e32 v69, v69
	v_exp_f32_e32 v70, v70
	v_exp_f32_e32 v71, v71
	v_exp_f32_e32 v72, v72
	v_exp_f32_e32 v73, v73
	v_exp_f32_e32 v74, v74
	v_exp_f32_e32 v75, v75
	v_exp_f32_e32 v76, v76
	v_exp_f32_e32 v77, v77
	v_exp_f32_e32 v78, v78
	v_exp_f32_e32 v79, v79
	v_add_f32_e32 v201, v80, v81
	v_add_f32_e32 v202, v82, v83
	v_add_f32_e32 v201, v201, v84
	v_add_f32_e32 v202, v202, v85
	v_add_f32_e32 v201, v201, v86
	v_add_f32_e32 v202, v202, v87
	v_add_f32_e32 v201, v201, v88
	v_add_f32_e32 v202, v202, v89
	v_add_f32_e32 v201, v201, v90
	v_add_f32_e32 v202, v202, v91
	v_add_f32_e32 v201, v201, v92
	v_add_f32_e32 v202, v202, v93
	v_add_f32_e32 v201, v201, v94
	v_add_f32_e32 v202, v202, v95
	v_add_f32_e32 v201, v201, v64
	v_add_f32_e32 v202, v202, v65
	v_add_f32_e32 v201, v201, v66
	v_add_f32_e32 v202, v202, v67
	v_add_f32_e32 v201, v201, v68
	v_add_f32_e32 v202, v202, v69
	v_add_f32_e32 v201, v201, v70
	v_add_f32_e32 v202, v202, v71
	v_add_f32_e32 v201, v201, v72
	v_add_f32_e32 v202, v202, v73
	v_add_f32_e32 v201, v201, v74
	v_add_f32_e32 v202, v202, v75
	v_add_f32_e32 v201, v201, v76
	v_add_f32_e32 v202, v202, v77
	v_add_f32_e32 v201, v201, v78
	v_add_f32_e32 v202, v202, v79
	v_add_f32_e32 v201, v201, v202
	v_mov_b32_e32 v202, v201
	v_cvt_pk_bf16_f32 v166, v80, v81
	v_cvt_pk_bf16_f32 v167, v82, v83
	v_cvt_pk_bf16_f32 v168, v84, v85
	v_cvt_pk_bf16_f32 v169, v86, v87
	v_cvt_pk_bf16_f32 v170, v88, v89
	v_cvt_pk_bf16_f32 v171, v90, v91
	v_cvt_pk_bf16_f32 v172, v92, v93
	v_cvt_pk_bf16_f32 v173, v94, v95
	v_cvt_pk_bf16_f32 v176, v64, v65
	v_cvt_pk_bf16_f32 v177, v66, v67
	v_cvt_pk_bf16_f32 v178, v68, v69
	v_cvt_pk_bf16_f32 v179, v70, v71
	v_cvt_pk_bf16_f32 v180, v72, v73
	v_cvt_pk_bf16_f32 v181, v74, v75
	v_cvt_pk_bf16_f32 v182, v76, v77
	v_cvt_pk_bf16_f32 v183, v78, v79
	s_nop 1
	v_permlane32_swap_b32_e32 v201, v202
	v_permlane32_swap_b32_e32 v166, v168
	v_permlane32_swap_b32_e32 v167, v169
	v_permlane32_swap_b32_e32 v170, v172
	v_permlane32_swap_b32_e32 v171, v173
	v_permlane32_swap_b32_e32 v176, v178
	v_permlane32_swap_b32_e32 v177, v179
	v_permlane32_swap_b32_e32 v180, v182
	v_permlane32_swap_b32_e32 v181, v183
	v_add_f32_e32 v201, v201, v202
	v_fma_f32 v175, v175, v213, v201
	s_cmp_lt_u32 s100, 130
	s_cbranch_scc0 .Lda_skipw_0
	s_waitcnt vmcnt(0)
	ds_write_b128 v197, v[134:137] offset:32768
	ds_write_b128 v197, v[138:141] offset:40960
	ds_write_b128 v200, v[142:145] offset:32768
	ds_write_b128 v200, v[146:149] offset:40960
	s_nop 1
; #define SBAR() __builtin_amdgcn_sched_barrier(0)
; __device__ __forceinline__ void qkt(f32x16& p0, f32x16& p1, const bf16_t* Ks, const bf16x8* qr, int r32, int hi) {
;   p0 = f32x16{}; p1 = f32x16{};
; #pragma unroll
;   for (int d0 = 0; d0 < 8; ++d0) { int cb = (d0 * 16 + hi * 8) * 2;
;     bf16x8 b0 = *reinterpret_cast<const bf16x8*>((const char*)Ks + KSWZ(r32, cb));
;     bf16x8 b1 = *reinterpret_cast<const bf16x8*>((const char*)Ks + KSWZ(32 + r32, cb));
;     p0 = __builtin_amdgcn_mfma_f32_32x32x16_bf16(b0, qr[d0], p0, 0, 0, 0);
;     p1 = __builtin_amdgcn_mfma_f32_32x32x16_bf16(b1, qr[d0], p1, 0, 0, 0); }
; }
; __device__ __forceinline__ int v_st(int k, int c) { const int kk = (k & ~0xC) | ((k & 4) << 1) | ((k & 8) >> 1); return ((kk >> 3) * 4 + (c >> 5)) * 512 + ((kk & 7) * 32 + (c & 31)) * 2; }
; __device__ __forceinline__ int v_rd_base(int lane) { return ((lane & 3) << 3) | (((lane >> 2) & 3) << 6) | (((lane >> 4) & 1) << 5) | (((lane >> 5) & 1) << 8); }
; template <int OFF> __device__ __forceinline__ s16x4 tr_read(int vb) {
;   s16x4 r; asm volatile("ds_read_b64_tr_b16 %0, %1 offset:%2" : "=&v"(r) : "v"(vb), "i"(OFF) : "memory"); return r;
; }
; template <int D0> __device__ __forceinline__ void pv_one(f32x16& od, int vb, bf16x8 pa0, bf16x8 pa1, bf16x8 pa2, bf16x8 pa3) {
;   const s16x4 l0 = tr_read<v_rd_off(D0, 0, 0)>(vb), h0 = tr_read<v_rd_off(D0, 0, 1)>(vb), l1 = tr_read<v_rd_off(D0, 1, 0)>(vb), h1 = tr_read<v_rd_off(D0, 1, 1)>(vb);
;   const s16x4 l2 = tr_read<v_rd_off(D0, 2, 0)>(vb), h2 = tr_read<v_rd_off(D0, 2, 1)>(vb), l3 = tr_read<v_rd_off(D0, 3, 0)>(vb), h3 = tr_read<v_rd_off(D0, 3, 1)>(vb);
;   asm volatile("s_waitcnt lgkmcnt(0)" ::: "memory"); SBAR();
;     ...
;   od = __builtin_amdgcn_mfma_f32_32x32x16_bf16(pa0, PK(l0, h0), od, 0, 0, 0);
;   od = __builtin_amdgcn_mfma_f32_32x32x16_bf16(pa1, PK(l1, h1), od, 0, 0, 0);
;   od = __builtin_amdgcn_mfma_f32_32x32x16_bf16(pa2, PK(l2, h2), od, 0, 0, 0);
;   od = __builtin_amdgcn_mfma_f32_32x32x16_bf16(pa3, PK(l3, h3), od, 0, 0, 0);
;     ...
; }
; __device__ __forceinline__ void pv_d0(f32x16* o, int vb, bf16x8 pa0, bf16x8 pa1, bf16x8 pa2, bf16x8 pa3) {
;   pv_one<0>(o[0], vb, pa0, pa1, pa2, pa3); pv_one<1>(o[1], vb, pa0, pa1, pa2, pa3); pv_one<2>(o[2], vb, pa0, pa1, pa2, pa3); pv_one<3>(o[3], vb, pa0, pa1, pa2, pa3);
.Lda_skipw_0:
	s_cmp_lt_u32 s100, 129
	s_cbranch_scc0 .Lda_skipl_0
	global_load_dwordx4 v[134:137], v[188:189], off
	global_load_dwordx4 v[138:141], v[190:191], off
	global_load_dwordx4 v[142:145], v[184:185], off
	global_load_dwordx4 v[146:149], v[186:187], off
	v_lshl_add_u64 v[184:185], v[184:185], 0, s[2:3]
	v_lshl_add_u64 v[186:187], v[186:187], 0, s[2:3]
	v_lshl_add_u64 v[188:189], v[188:189], 0, s[2:3]
	v_lshl_add_u64 v[190:191], v[190:191], 0, s[2:3]
.Lda_skipl_0:
	s_add_u32 s100, s100, 1
	s_cmp_lt_u32 s100, 132
	s_cbranch_scc0 .Lda_skipk_0
	ds_read_b128 v[150:153], v204 offset:16384
	ds_read_b128 v[154:157], v204 offset:24576
	ds_read_b128 v[158:161], v205 offset:16384
	ds_read_b128 v[162:165], v205 offset:24576
	ds_read_b128 v[228:231], v206 offset:16384
	ds_read_b128 v[232:235], v206 offset:24576
	ds_read_b128 v[236:239], v207 offset:16384
	ds_read_b128 v[240:243], v207 offset:24576
.Lda_skipk_0:
	s_barrier
	s_waitcnt lgkmcnt(6)
	v_mfma_f32_32x32x16_bf16 v[80:95], v[150:153], v[130:133], 0
	v_mfma_f32_32x32x16_bf16 v[64:79], v[154:157], v[130:133], 0
	ds_read_b128 v[150:153], v208 offset:16384
	ds_read_b128 v[154:157], v208 offset:24576
	s_waitcnt lgkmcnt(6)
	v_mfma_f32_32x32x16_bf16 v[80:95], v[158:161], v[126:129], v[80:95]
	v_mfma_f32_32x32x16_bf16 v[64:79], v[162:165], v[126:129], v[64:79]
	ds_read_b128 v[158:161], v209 offset:16384
	ds_read_b128 v[162:165], v209 offset:24576
	s_waitcnt lgkmcnt(6)
	v_mfma_f32_32x32x16_bf16 v[80:95], v[228:231], v[122:125], v[80:95]
	v_mfma_f32_32x32x16_bf16 v[64:79], v[232:235], v[122:125], v[64:79]
	ds_read_b128 v[228:231], v210 offset:16384
	ds_read_b128 v[232:235], v210 offset:24576
	s_waitcnt lgkmcnt(6)
	v_mfma_f32_32x32x16_bf16 v[80:95], v[236:239], v[118:121], v[80:95]
	v_mfma_f32_32x32x16_bf16 v[64:79], v[240:243], v[118:121], v[64:79]
	ds_read_b128 v[236:239], v211 offset:16384
	ds_read_b128 v[240:243], v211 offset:24576
	s_waitcnt lgkmcnt(6)
	v_mfma_f32_32x32x16_bf16 v[80:95], v[150:153], v[114:117], v[80:95]
	v_mfma_f32_32x32x16_bf16 v[64:79], v[154:157], v[114:117], v[64:79]
	ds_read_b64_tr_b16 v[150:151], v196 offset:0
	ds_read_b64_tr_b16 v[152:153], v196 offset:2048
	ds_read_b64_tr_b16 v[154:155], v196 offset:4096
	ds_read_b64_tr_b16 v[156:157], v196 offset:6144
	s_waitcnt lgkmcnt(8)
	v_mfma_f32_32x32x16_bf16 v[80:95], v[158:161], v[110:113], v[80:95]
	v_mfma_f32_32x32x16_bf16 v[64:79], v[162:165], v[110:113], v[64:79]
	ds_read_b64_tr_b16 v[158:159], v196 offset:8192
	ds_read_b64_tr_b16 v[160:161], v196 offset:10240
	ds_read_b64_tr_b16 v[162:163], v196 offset:12288
	ds_read_b64_tr_b16 v[164:165], v196 offset:14336
	s_waitcnt lgkmcnt(10)
	v_mfma_f32_32x32x16_bf16 v[80:95], v[228:231], v[106:109], v[80:95]
	v_mfma_f32_32x32x16_bf16 v[64:79], v[232:235], v[106:109], v[64:79]
	ds_read_b64_tr_b16 v[228:229], v196 offset:512
	ds_read_b64_tr_b16 v[230:231], v196 offset:2560
	ds_read_b64_tr_b16 v[232:233], v196 offset:4608
	ds_read_b64_tr_b16 v[234:235], v196 offset:6656
	s_waitcnt lgkmcnt(12)
	v_mfma_f32_32x32x16_bf16 v[80:95], v[236:239], v[102:105], v[80:95]
	v_mfma_f32_32x32x16_bf16 v[64:79], v[240:243], v[102:105], v[64:79]
	ds_read_b64_tr_b16 v[236:237], v196 offset:8704
	ds_read_b64_tr_b16 v[238:239], v196 offset:10752
	s_waitcnt lgkmcnt(12)
	v_mfma_f32_32x32x16_bf16 v[0:15], v[166:169], v[150:153], v[0:15]
	ds_read_b64_tr_b16 v[240:241], v196 offset:12800
	ds_read_b64_tr_b16 v[242:243], v196 offset:14848
	s_waitcnt lgkmcnt(12)
	v_mfma_f32_32x32x16_bf16 v[0:15], v[170:173], v[154:157], v[0:15]
	ds_read_b64_tr_b16 v[150:151], v196 offset:1024
	ds_read_b64_tr_b16 v[152:153], v196 offset:3072
	s_waitcnt lgkmcnt(12)
	v_mfma_f32_32x32x16_bf16 v[0:15], v[176:179], v[158:161], v[0:15]
	ds_read_b64_tr_b16 v[154:155], v196 offset:5120
	ds_read_b64_tr_b16 v[156:157], v196 offset:7168
	s_waitcnt lgkmcnt(12)
	v_mfma_f32_32x32x16_bf16 v[0:15], v[180:183], v[162:165], v[0:15]
	ds_read_b64_tr_b16 v[158:159], v196 offset:9216
	ds_read_b64_tr_b16 v[160:161], v196 offset:11264
	s_waitcnt lgkmcnt(12)
	v_mfma_f32_32x32x16_bf16 v[48:63], v[166:169], v[228:231], v[48:63]
	ds_read_b64_tr_b16 v[162:163], v196 offset:13312
	ds_read_b64_tr_b16 v[164:165], v196 offset:15360
	s_waitcnt lgkmcnt(12)
	v_mfma_f32_32x32x16_bf16 v[48:63], v[170:173], v[232:235], v[48:63]
	ds_read_b64_tr_b16 v[228:229], v196 offset:1536
	ds_read_b64_tr_b16 v[230:231], v196 offset:3584
	s_waitcnt lgkmcnt(12)
	v_mfma_f32_32x32x16_bf16 v[48:63], v[176:179], v[236:239], v[48:63]
	ds_read_b64_tr_b16 v[232:233], v196 offset:5632
	ds_read_b64_tr_b16 v[234:235], v196 offset:7680
	s_waitcnt lgkmcnt(12)
	v_mfma_f32_32x32x16_bf16 v[48:63], v[180:183], v[240:243], v[48:63]
	ds_read_b64_tr_b16 v[236:237], v196 offset:9728
	ds_read_b64_tr_b16 v[238:239], v196 offset:11776
	s_waitcnt lgkmcnt(12)
	v_mfma_f32_32x32x16_bf16 v[32:47], v[166:169], v[150:153], v[32:47]
	ds_read_b64_tr_b16 v[240:241], v196 offset:13824
	ds_read_b64_tr_b16 v[242:243], v196 offset:15872
	s_waitcnt lgkmcnt(12)
	v_mfma_f32_32x32x16_bf16 v[32:47], v[170:173], v[154:157], v[32:47]
	s_waitcnt lgkmcnt(10)
	v_mfma_f32_32x32x16_bf16 v[32:47], v[176:179], v[158:161], v[32:47]
	s_waitcnt lgkmcnt(8)
	v_mfma_f32_32x32x16_bf16 v[32:47], v[180:183], v[162:165], v[32:47]
	s_waitcnt lgkmcnt(6)
	v_mfma_f32_32x32x16_bf16 v[16:31], v[166:169], v[228:231], v[16:31]
	s_waitcnt lgkmcnt(4)
	v_mfma_f32_32x32x16_bf16 v[16:31], v[170:173], v[232:235], v[16:31]
	s_waitcnt lgkmcnt(2)
	v_mfma_f32_32x32x16_bf16 v[16:31], v[176:179], v[236:239], v[16:31]
	s_waitcnt lgkmcnt(0)
	v_mfma_f32_32x32x16_bf16 v[16:31], v[180:183], v[240:243], v[16:31]
	s_barrier
; __device__ __forceinline__ void partialSM(f32x16& p0, f32x16& p1, float& m_reg, float& mn, float& alpha) {
;   constexpr float C = SCALE * 1.4426950408889634f;
;   float pmax = p0[0];
; #pragma unroll
;   for (int r = 1; r < 16; ++r) pmax = fmaxf(pmax, p0[r]);
; #pragma unroll
;   for (int r = 0; r < 16; ++r) pmax = fmaxf(pmax, p1[r]);
;   { auto rr = __builtin_amdgcn_permlane32_swap(__float_as_uint(pmax), __float_as_uint(pmax), false, false);
;     pmax = fmaxf(__uint_as_float(rr[0]), __uint_as_float(rr[1])); }
;   if (__builtin_expect(__all(pmax - m_reg <= THR / SCALE), 1)) { mn = m_reg; alpha = 1.f; }
;   else { mn = fmaxf(m_reg, pmax); alpha = __builtin_amdgcn_exp2f((m_reg - mn) * C); m_reg = mn; }
;   float mnC = -mn * C;
; #pragma unroll
;   for (int r = 0; r < 16; ++r) p0[r] = fmaf(p0[r], C, mnC);
; #pragma unroll
;   for (int r = 0; r < 16; ++r) p1[r] = fmaf(p1[r], C, mnC);
; #pragma unroll
;   for (int r = 0; r < 16; ++r) p0[r] = __builtin_amdgcn_exp2f(p0[r]);
; }
; __device__ __forceinline__ void finishSM(f32x16& p0, f32x16& p1, float alpha, float& l_reg, bf16x8& pa0, bf16x8& pa1, bf16x8& pa2, bf16x8& pa3) {
; #pragma unroll
;   for (int r = 0; r < 16; ++r) p1[r] = __builtin_amdgcn_exp2f(p1[r]);
;   float ps = 0;
; #pragma unroll
;   for (int r = 0; r < 16; ++r) ps += p0[r];
; #pragma unroll
;   for (int r = 0; r < 16; ++r) ps += p1[r];
;   { auto rr = __builtin_amdgcn_permlane32_swap(__float_as_uint(ps), __float_as_uint(ps), false, false);
;     ps = __uint_as_float(rr[0]) + __uint_as_float(rr[1]); }
;   l_reg = l_reg * alpha + ps;
;     ...
;   PK4(p0, 0, pa0); PK4(p0, 8, pa1); PK4(p1, 0, pa2); PK4(p1, 8, pa3);
;     ...
; }
	v_max3_f32 v201, v80, v81, v82
	v_max3_f32 v202, v64, v65, v66
	v_max3_f32 v201, v201, v83, v84
	v_max3_f32 v202, v202, v67, v68
	v_max3_f32 v201, v201, v85, v86
	v_max3_f32 v202, v202, v69, v70
	v_max3_f32 v201, v201, v87, v88
	v_max3_f32 v202, v202, v71, v72
	v_max3_f32 v201, v201, v89, v90
	v_max3_f32 v202, v202, v73, v74
	v_max3_f32 v201, v201, v91, v92
	v_max3_f32 v202, v202, v75, v76
	v_max3_f32 v201, v201, v93, v94
	v_max3_f32 v202, v202, v77, v78
	v_max3_f32 v201, v201, v95, v79
	v_max_f32_e32 v201, v201, v202
	v_mov_b32_e32 v202, v201
	s_nop 1
	v_permlane32_swap_b32_e32 v201, v202
	s_nop 0
	v_max_f32_e32 v212, v201, v202
	v_sub_f32_e32 v201, v212, v174
	v_cmp_ge_f32_e32 vcc, s86, v201
	v_max_f32_e32 v202, v174, v212
	v_sub_f32_e32 v215, v174, v202
	v_mul_f32_e32 v215, s92, v215
	s_nop 1
	s_cmp_eq_u64 vcc, exec
	s_cselect_b64 s[42:43], -1, 0
	v_exp_f32_e32 v213, v215
	s_nop 0
	v_cndmask_b32_e64 v174, v202, v174, s[42:43]
	v_cndmask_b32_e64 v213, v213, 1.0, s[42:43]
	v_mul_f32_e32 v214, 0xbe0293ee, v174
	s_nop 0
	v_cmp_gt_f32_e32 vcc, 1.0, v213
	v_fma_f32 v80, v80, s92, v214
	v_fma_f32 v81, v81, s92, v214
	v_fma_f32 v82, v82, s92, v214
	v_fma_f32 v83, v83, s92, v214
	v_fma_f32 v84, v84, s92, v214
	v_fma_f32 v85, v85, s92, v214
	v_fma_f32 v86, v86, s92, v214
	v_fma_f32 v87, v87, s92, v214
	v_fma_f32 v88, v88, s92, v214
	v_fma_f32 v89, v89, s92, v214
	v_fma_f32 v90, v90, s92, v214
	v_fma_f32 v91, v91, s92, v214
	v_fma_f32 v92, v92, s92, v214
	v_fma_f32 v93, v93, s92, v214
	v_fma_f32 v94, v94, s92, v214
	v_fma_f32 v95, v95, s92, v214
	v_fma_f32 v64, v64, s92, v214
	v_fma_f32 v65, v65, s92, v214
	v_fma_f32 v66, v66, s92, v214
	v_fma_f32 v67, v67, s92, v214
	v_fma_f32 v68, v68, s92, v214
	v_fma_f32 v69, v69, s92, v214
	v_fma_f32 v70, v70, s92, v214
	v_fma_f32 v71, v71, s92, v214
	v_fma_f32 v72, v72, s92, v214
	v_fma_f32 v73, v73, s92, v214
	v_fma_f32 v74, v74, s92, v214
	v_fma_f32 v75, v75, s92, v214
	v_fma_f32 v76, v76, s92, v214
	v_fma_f32 v77, v77, s92, v214
	v_fma_f32 v78, v78, s92, v214
	v_fma_f32 v79, v79, s92, v214
	s_cbranch_vccz .Lda_noresc_1
	s_and_saveexec_b64 s[34:35], s[40:41]
	ds_write_b32 v199, v213 offset:128
	s_or_b64 exec, exec, s[34:35]
	s_waitcnt lgkmcnt(0)
	v_add_u32_e32 v215, v99, v96
	ds_read_b128 v[228:231], v215 offset:128
	ds_read_b128 v[232:235], v215 offset:160
	ds_read_b128 v[236:239], v215 offset:192
	ds_read_b128 v[240:243], v215 offset:224
	s_waitcnt lgkmcnt(0)
	v_pk_mul_f32 v[0:1], v[0:1], v[228:229]
	v_pk_mul_f32 v[2:3], v[2:3], v[230:231]
	v_pk_mul_f32 v[4:5], v[4:5], v[232:233]
	v_pk_mul_f32 v[6:7], v[6:7], v[234:235]
	v_pk_mul_f32 v[8:9], v[8:9], v[236:237]
	v_pk_mul_f32 v[10:11], v[10:11], v[238:239]
	v_pk_mul_f32 v[12:13], v[12:13], v[240:241]
	v_pk_mul_f32 v[14:15], v[14:15], v[242:243]
	v_pk_mul_f32 v[48:49], v[48:49], v[228:229]
	v_pk_mul_f32 v[50:51], v[50:51], v[230:231]
	v_pk_mul_f32 v[52:53], v[52:53], v[232:233]
	v_pk_mul_f32 v[54:55], v[54:55], v[234:235]
	v_pk_mul_f32 v[56:57], v[56:57], v[236:237]
	v_pk_mul_f32 v[58:59], v[58:59], v[238:239]
	v_pk_mul_f32 v[60:61], v[60:61], v[240:241]
	v_pk_mul_f32 v[62:63], v[62:63], v[242:243]
	v_pk_mul_f32 v[32:33], v[32:33], v[228:229]
	v_pk_mul_f32 v[34:35], v[34:35], v[230:231]
	v_pk_mul_f32 v[36:37], v[36:37], v[232:233]
	v_pk_mul_f32 v[38:39], v[38:39], v[234:235]
	v_pk_mul_f32 v[40:41], v[40:41], v[236:237]
	v_pk_mul_f32 v[42:43], v[42:43], v[238:239]
	v_pk_mul_f32 v[44:45], v[44:45], v[240:241]
	v_pk_mul_f32 v[46:47], v[46:47], v[242:243]
	v_pk_mul_f32 v[16:17], v[16:17], v[228:229]
	v_pk_mul_f32 v[18:19], v[18:19], v[230:231]
	v_pk_mul_f32 v[20:21], v[20:21], v[232:233]
	v_pk_mul_f32 v[22:23], v[22:23], v[234:235]
	v_pk_mul_f32 v[24:25], v[24:25], v[236:237]
	v_pk_mul_f32 v[26:27], v[26:27], v[238:239]
	v_pk_mul_f32 v[28:29], v[28:29], v[240:241]
	v_pk_mul_f32 v[30:31], v[30:31], v[242:243]
.Lda_noresc_1:
	v_exp_f32_e32 v80, v80
	v_exp_f32_e32 v81, v81
	v_exp_f32_e32 v82, v82
	v_exp_f32_e32 v83, v83
	v_exp_f32_e32 v84, v84
	v_exp_f32_e32 v85, v85
	v_exp_f32_e32 v86, v86
	v_exp_f32_e32 v87, v87
	v_exp_f32_e32 v88, v88
	v_exp_f32_e32 v89, v89
	v_exp_f32_e32 v90, v90
	v_exp_f32_e32 v91, v91
	v_exp_f32_e32 v92, v92
	v_exp_f32_e32 v93, v93
	v_exp_f32_e32 v94, v94
	v_exp_f32_e32 v95, v95
	v_exp_f32_e32 v64, v64
	v_exp_f32_e32 v65, v65
	v_exp_f32_e32 v66, v66
	v_exp_f32_e32 v67, v67
	v_exp_f32_e32 v68, v68
	v_exp_f32_e32 v69, v69
	v_exp_f32_e32 v70, v70
	v_exp_f32_e32 v71, v71
	v_exp_f32_e32 v72, v72
	v_exp_f32_e32 v73, v73
	v_exp_f32_e32 v74, v74
	v_exp_f32_e32 v75, v75
	v_exp_f32_e32 v76, v76
	v_exp_f32_e32 v77, v77
	v_exp_f32_e32 v78, v78
	v_exp_f32_e32 v79, v79
	v_add_f32_e32 v201, v80, v81
	v_add_f32_e32 v202, v82, v83
	v_add_f32_e32 v201, v201, v84
	v_add_f32_e32 v202, v202, v85
	v_add_f32_e32 v201, v201, v86
	v_add_f32_e32 v202, v202, v87
	v_add_f32_e32 v201, v201, v88
	v_add_f32_e32 v202, v202, v89
	v_add_f32_e32 v201, v201, v90
	v_add_f32_e32 v202, v202, v91
	v_add_f32_e32 v201, v201, v92
	v_add_f32_e32 v202, v202, v93
	v_add_f32_e32 v201, v201, v94
	v_add_f32_e32 v202, v202, v95
	v_add_f32_e32 v201, v201, v64
	v_add_f32_e32 v202, v202, v65
	v_add_f32_e32 v201, v201, v66
	v_add_f32_e32 v202, v202, v67
	v_add_f32_e32 v201, v201, v68
	v_add_f32_e32 v202, v202, v69
	v_add_f32_e32 v201, v201, v70
	v_add_f32_e32 v202, v202, v71
	v_add_f32_e32 v201, v201, v72
	v_add_f32_e32 v202, v202, v73
	v_add_f32_e32 v201, v201, v74
	v_add_f32_e32 v202, v202, v75
	v_add_f32_e32 v201, v201, v76
	v_add_f32_e32 v202, v202, v77
	v_add_f32_e32 v201, v201, v78
	v_add_f32_e32 v202, v202, v79
	v_add_f32_e32 v201, v201, v202
	v_mov_b32_e32 v202, v201
	v_cvt_pk_bf16_f32 v166, v80, v81
	v_cvt_pk_bf16_f32 v167, v82, v83
	v_cvt_pk_bf16_f32 v168, v84, v85
	v_cvt_pk_bf16_f32 v169, v86, v87
	v_cvt_pk_bf16_f32 v170, v88, v89
	v_cvt_pk_bf16_f32 v171, v90, v91
	v_cvt_pk_bf16_f32 v172, v92, v93
	v_cvt_pk_bf16_f32 v173, v94, v95
	v_cvt_pk_bf16_f32 v176, v64, v65
	v_cvt_pk_bf16_f32 v177, v66, v67
	v_cvt_pk_bf16_f32 v178, v68, v69
	v_cvt_pk_bf16_f32 v179, v70, v71
	v_cvt_pk_bf16_f32 v180, v72, v73
	v_cvt_pk_bf16_f32 v181, v74, v75
	v_cvt_pk_bf16_f32 v182, v76, v77
	v_cvt_pk_bf16_f32 v183, v78, v79
	s_nop 1
	v_permlane32_swap_b32_e32 v201, v202
	v_permlane32_swap_b32_e32 v166, v168
	v_permlane32_swap_b32_e32 v167, v169
	v_permlane32_swap_b32_e32 v170, v172
	v_permlane32_swap_b32_e32 v171, v173
	v_permlane32_swap_b32_e32 v176, v178
	v_permlane32_swap_b32_e32 v177, v179
	v_permlane32_swap_b32_e32 v180, v182
	v_permlane32_swap_b32_e32 v181, v183
	v_add_f32_e32 v201, v201, v202
	v_fma_f32 v175, v175, v213, v201
	s_cmp_lt_u32 s100, 130
	s_cbranch_scc0 .Lda_skipw_1
	s_waitcnt vmcnt(0)
	ds_write_b128 v197, v[134:137] offset:49152
	ds_write_b128 v197, v[138:141] offset:57344
	ds_write_b128 v200, v[142:145] offset:49152
	ds_write_b128 v200, v[146:149] offset:57344
	s_nop 1

; #define SBAR() __builtin_amdgcn_sched_barrier(0)
; __device__ __forceinline__ void qkt(f32x16& p0, f32x16& p1, const bf16_t* Ks, const bf16x8* qr, int r32, int hi) {
;   p0 = f32x16{}; p1 = f32x16{};
; #pragma unroll
;   for (int d0 = 0; d0 < 8; ++d0) { int cb = (d0 * 16 + hi * 8) * 2;
;     bf16x8 b0 = *reinterpret_cast<const bf16x8*>((const char*)Ks + KSWZ(r32, cb));
;     bf16x8 b1 = *reinterpret_cast<const bf16x8*>((const char*)Ks + KSWZ(32 + r32, cb));
;     p0 = __builtin_amdgcn_mfma_f32_32x32x16_bf16(b0, qr[d0], p0, 0, 0, 0);
;     p1 = __builtin_amdgcn_mfma_f32_32x32x16_bf16(b1, qr[d0], p1, 0, 0, 0); }
; }
; __device__ __forceinline__ int v_st(int k, int c) { const int kk = (k & ~0xC) | ((k & 4) << 1) | ((k & 8) >> 1); return ((kk >> 3) * 4 + (c >> 5)) * 512 + ((kk & 7) * 32 + (c & 31)) * 2; }
; __device__ __forceinline__ int v_rd_base(int lane) { return ((lane & 3) << 3) | (((lane >> 2) & 3) << 6) | (((lane >> 4) & 1) << 5) | (((lane >> 5) & 1) << 8); }
; template <int OFF> __device__ __forceinline__ s16x4 tr_read(int vb) {
;   s16x4 r; asm volatile("ds_read_b64_tr_b16 %0, %1 offset:%2" : "=&v"(r) : "v"(vb), "i"(OFF) : "memory"); return r;
; }
; template <int D0> __device__ __forceinline__ void pv_one(f32x16& od, int vb, bf16x8 pa0, bf16x8 pa1, bf16x8 pa2, bf16x8 pa3) {
;   const s16x4 l0 = tr_read<v_rd_off(D0, 0, 0)>(vb), h0 = tr_read<v_rd_off(D0, 0, 1)>(vb), l1 = tr_read<v_rd_off(D0, 1, 0)>(vb), h1 = tr_read<v_rd_off(D0, 1, 1)>(vb);
;   const s16x4 l2 = tr_read<v_rd_off(D0, 2, 0)>(vb), h2 = tr_read<v_rd_off(D0, 2, 1)>(vb), l3 = tr_read<v_rd_off(D0, 3, 0)>(vb), h3 = tr_read<v_rd_off(D0, 3, 1)>(vb);
;   asm volatile("s_waitcnt lgkmcnt(0)" ::: "memory"); SBAR();
;     ...
;   od = __builtin_amdgcn_mfma_f32_32x32x16_bf16(pa0, PK(l0, h0), od, 0, 0, 0);
;   od = __builtin_amdgcn_mfma_f32_32x32x16_bf16(pa1, PK(l1, h1), od, 0, 0, 0);
;   od = __builtin_amdgcn_mfma_f32_32x32x16_bf16(pa2, PK(l2, h2), od, 0, 0, 0);
;   od = __builtin_amdgcn_mfma_f32_32x32x16_bf16(pa3, PK(l3, h3), od, 0, 0, 0);
;     ...
; }
; __device__ __forceinline__ void pv_d0(f32x16* o, int vb, bf16x8 pa0, bf16x8 pa1, bf16x8 pa2, bf16x8 pa3) {
;   pv_one<0>(o[0], vb, pa0, pa1, pa2, pa3); pv_one<1>(o[1], vb, pa0, pa1, pa2, pa3); pv_one<2>(o[2], vb, pa0, pa1, pa2, pa3); pv_one<3>(o[3], vb, pa0, pa1, pa2, pa3);
.Lda_skipl_1:
	s_add_u32 s100, s100, 1
	s_cmp_lt_u32 s100, 132
	s_cbranch_scc0 .Lda_skipk_1
	ds_read_b128 v[150:153], v204 offset:32768
	ds_read_b128 v[154:157], v204 offset:40960
	ds_read_b128 v[158:161], v205 offset:32768
	ds_read_b128 v[162:165], v205 offset:40960
	ds_read_b128 v[228:231], v206 offset:32768
	ds_read_b128 v[232:235], v206 offset:40960
	ds_read_b128 v[236:239], v207 offset:32768
	ds_read_b128 v[240:243], v207 offset:40960
.Lda_skipk_1:
	s_barrier
	s_waitcnt lgkmcnt(6)
	v_mfma_f32_32x32x16_bf16 v[80:95], v[150:153], v[130:133], 0
	v_mfma_f32_32x32x16_bf16 v[64:79], v[154:157], v[130:133], 0
	ds_read_b128 v[150:153], v208 offset:32768
	ds_read_b128 v[154:157], v208 offset:40960
	s_waitcnt lgkmcnt(6)
	v_mfma_f32_32x32x16_bf16 v[80:95], v[158:161], v[126:129], v[80:95]
	v_mfma_f32_32x32x16_bf16 v[64:79], v[162:165], v[126:129], v[64:79]
	ds_read_b128 v[158:161], v209 offset:32768
	ds_read_b128 v[162:165], v209 offset:40960
	s_waitcnt lgkmcnt(6)
	v_mfma_f32_32x32x16_bf16 v[80:95], v[228:231], v[122:125], v[80:95]
	v_mfma_f32_32x32x16_bf16 v[64:79], v[232:235], v[122:125], v[64:79]
	ds_read_b128 v[228:231], v210 offset:32768
	ds_read_b128 v[232:235], v210 offset:40960
	s_waitcnt lgkmcnt(6)
	v_mfma_f32_32x32x16_bf16 v[80:95], v[236:239], v[118:121], v[80:95]
	v_mfma_f32_32x32x16_bf16 v[64:79], v[240:243], v[118:121], v[64:79]
	ds_read_b128 v[236:239], v211 offset:32768
	ds_read_b128 v[240:243], v211 offset:40960
	s_waitcnt lgkmcnt(6)
	v_mfma_f32_32x32x16_bf16 v[80:95], v[150:153], v[114:117], v[80:95]
	v_mfma_f32_32x32x16_bf16 v[64:79], v[154:157], v[114:117], v[64:79]
	ds_read_b64_tr_b16 v[150:151], v196 offset:16384
	ds_read_b64_tr_b16 v[152:153], v196 offset:18432
	ds_read_b64_tr_b16 v[154:155], v196 offset:20480
	ds_read_b64_tr_b16 v[156:157], v196 offset:22528
	s_waitcnt lgkmcnt(8)
	v_mfma_f32_32x32x16_bf16 v[80:95], v[158:161], v[110:113], v[80:95]
	v_mfma_f32_32x32x16_bf16 v[64:79], v[162:165], v[110:113], v[64:79]
	ds_read_b64_tr_b16 v[158:159], v196 offset:24576
	ds_read_b64_tr_b16 v[160:161], v196 offset:26624
	ds_read_b64_tr_b16 v[162:163], v196 offset:28672
	ds_read_b64_tr_b16 v[164:165], v196 offset:30720
	s_waitcnt lgkmcnt(10)
	v_mfma_f32_32x32x16_bf16 v[80:95], v[228:231], v[106:109], v[80:95]
	v_mfma_f32_32x32x16_bf16 v[64:79], v[232:235], v[106:109], v[64:79]
	ds_read_b64_tr_b16 v[228:229], v196 offset:16896
	ds_read_b64_tr_b16 v[230:231], v196 offset:18944
	ds_read_b64_tr_b16 v[232:233], v196 offset:20992
	ds_read_b64_tr_b16 v[234:235], v196 offset:23040
	s_waitcnt lgkmcnt(12)
	v_mfma_f32_32x32x16_bf16 v[80:95], v[236:239], v[102:105], v[80:95]
	v_mfma_f32_32x32x16_bf16 v[64:79], v[240:243], v[102:105], v[64:79]
	ds_read_b64_tr_b16 v[236:237], v196 offset:25088
	ds_read_b64_tr_b16 v[238:239], v196 offset:27136
	s_waitcnt lgkmcnt(12)
	v_mfma_f32_32x32x16_bf16 v[0:15], v[166:169], v[150:153], v[0:15]
	ds_read_b64_tr_b16 v[240:241], v196 offset:29184
	ds_read_b64_tr_b16 v[242:243], v196 offset:31232
	s_waitcnt lgkmcnt(12)
	v_mfma_f32_32x32x16_bf16 v[0:15], v[170:173], v[154:157], v[0:15]
	ds_read_b64_tr_b16 v[150:151], v196 offset:17408
	ds_read_b64_tr_b16 v[152:153], v196 offset:19456
	s_waitcnt lgkmcnt(12)
	v_mfma_f32_32x32x16_bf16 v[0:15], v[176:179], v[158:161], v[0:15]
	ds_read_b64_tr_b16 v[154:155], v196 offset:21504
	ds_read_b64_tr_b16 v[156:157], v196 offset:23552
	s_waitcnt lgkmcnt(12)
	v_mfma_f32_32x32x16_bf16 v[0:15], v[180:183], v[162:165], v[0:15]
	ds_read_b64_tr_b16 v[158:159], v196 offset:25600
	ds_read_b64_tr_b16 v[160:161], v196 offset:27648
	s_waitcnt lgkmcnt(12)
	v_mfma_f32_32x32x16_bf16 v[48:63], v[166:169], v[228:231], v[48:63]
	ds_read_b64_tr_b16 v[162:163], v196 offset:29696
	ds_read_b64_tr_b16 v[164:165], v196 offset:31744
	s_waitcnt lgkmcnt(12)
	v_mfma_f32_32x32x16_bf16 v[48:63], v[170:173], v[232:235], v[48:63]
	ds_read_b64_tr_b16 v[228:229], v196 offset:17920
	ds_read_b64_tr_b16 v[230:231], v196 offset:19968
	s_waitcnt lgkmcnt(12)
	v_mfma_f32_32x32x16_bf16 v[48:63], v[176:179], v[236:239], v[48:63]
	ds_read_b64_tr_b16 v[232:233], v196 offset:22016
	ds_read_b64_tr_b16 v[234:235], v196 offset:24064
	s_waitcnt lgkmcnt(12)
	v_mfma_f32_32x32x16_bf16 v[48:63], v[180:183], v[240:243], v[48:63]
	ds_read_b64_tr_b16 v[236:237], v196 offset:26112
	ds_read_b64_tr_b16 v[238:239], v196 offset:28160
	s_waitcnt lgkmcnt(12)
	v_mfma_f32_32x32x16_bf16 v[32:47], v[166:169], v[150:153], v[32:47]
	ds_read_b64_tr_b16 v[240:241], v196 offset:30208
	ds_read_b64_tr_b16 v[242:243], v196 offset:32256
	s_waitcnt lgkmcnt(12)
	v_mfma_f32_32x32x16_bf16 v[32:47], v[170:173], v[154:157], v[32:47]
	s_waitcnt lgkmcnt(10)
	v_mfma_f32_32x32x16_bf16 v[32:47], v[176:179], v[158:161], v[32:47]
	s_waitcnt lgkmcnt(8)
	v_mfma_f32_32x32x16_bf16 v[32:47], v[180:183], v[162:165], v[32:47]
	s_waitcnt lgkmcnt(6)
	v_mfma_f32_32x32x16_bf16 v[16:31], v[166:169], v[228:231], v[16:31]
	s_waitcnt lgkmcnt(4)
	v_mfma_f32_32x32x16_bf16 v[16:31], v[170:173], v[232:235], v[16:31]
	s_waitcnt lgkmcnt(2)
	v_mfma_f32_32x32x16_bf16 v[16:31], v[176:179], v[236:239], v[16:31]
	s_waitcnt lgkmcnt(0)
	v_mfma_f32_32x32x16_bf16 v[16:31], v[180:183], v[240:243], v[16:31]
	s_barrier
; __device__ __forceinline__ void partialSM(f32x16& p0, f32x16& p1, float& m_reg, float& mn, float& alpha) {
;   constexpr float C = SCALE * 1.4426950408889634f;
;   float pmax = p0[0];
; #pragma unroll
;   for (int r = 1; r < 16; ++r) pmax = fmaxf(pmax, p0[r]);
; #pragma unroll
;   for (int r = 0; r < 16; ++r) pmax = fmaxf(pmax, p1[r]);
;   { auto rr = __builtin_amdgcn_permlane32_swap(__float_as_uint(pmax), __float_as_uint(pmax), false, false);
;     pmax = fmaxf(__uint_as_float(rr[0]), __uint_as_float(rr[1])); }
;   if (__builtin_expect(__all(pmax - m_reg <= THR / SCALE), 1)) { mn = m_reg; alpha = 1.f; }
;   else { mn = fmaxf(m_reg, pmax); alpha = __builtin_amdgcn_exp2f((m_reg - mn) * C); m_reg = mn; }
;   float mnC = -mn * C;
; #pragma unroll
;   for (int r = 0; r < 16; ++r) p0[r] = fmaf(p0[r], C, mnC);
; #pragma unroll
;   for (int r = 0; r < 16; ++r) p1[r] = fmaf(p1[r], C, mnC);
; #pragma unroll
;   for (int r = 0; r < 16; ++r) p0[r] = __builtin_amdgcn_exp2f(p0[r]);
; }
; __device__ __forceinline__ void finishSM(f32x16& p0, f32x16& p1, float alpha, float& l_reg, bf16x8& pa0, bf16x8& pa1, bf16x8& pa2, bf16x8& pa3) {
; #pragma unroll
;   for (int r = 0; r < 16; ++r) p1[r] = __builtin_amdgcn_exp2f(p1[r]);
;   float ps = 0;
; #pragma unroll
;   for (int r = 0; r < 16; ++r) ps += p0[r];
; #pragma unroll
;   for (int r = 0; r < 16; ++r) ps += p1[r];
;   { auto rr = __builtin_amdgcn_permlane32_swap(__float_as_uint(ps), __float_as_uint(ps), false, false);
;     ps = __uint_as_float(rr[0]) + __uint_as_float(rr[1]); }
;   l_reg = l_reg * alpha + ps;
;     ...
;   PK4(p0, 0, pa0); PK4(p0, 8, pa1); PK4(p1, 0, pa2); PK4(p1, 8, pa3);
;     ...
; }
	v_max3_f32 v201, v80, v81, v82
	v_max3_f32 v202, v64, v65, v66
	v_max3_f32 v201, v201, v83, v84
	v_max3_f32 v202, v202, v67, v68
	v_max3_f32 v201, v201, v85, v86
	v_max3_f32 v202, v202, v69, v70
	v_max3_f32 v201, v201, v87, v88
	v_max3_f32 v202, v202, v71, v72
	v_max3_f32 v201, v201, v89, v90
	v_max3_f32 v202, v202, v73, v74
	v_max3_f32 v201, v201, v91, v92
	v_max3_f32 v202, v202, v75, v76
	v_max3_f32 v201, v201, v93, v94
	v_max3_f32 v202, v202, v77, v78
	v_max3_f32 v201, v201, v95, v79
	v_max_f32_e32 v201, v201, v202
	v_mov_b32_e32 v202, v201
	s_nop 1
	v_permlane32_swap_b32_e32 v201, v202
	s_nop 0
	v_max_f32_e32 v212, v201, v202
	v_sub_f32_e32 v201, v212, v174
	v_cmp_ge_f32_e32 vcc, s86, v201
	v_max_f32_e32 v202, v174, v212
	v_sub_f32_e32 v215, v174, v202
	v_mul_f32_e32 v215, s92, v215
	s_nop 1
	s_cmp_eq_u64 vcc, exec
	s_cselect_b64 s[42:43], -1, 0
	v_exp_f32_e32 v213, v215
	s_nop 0
	v_cndmask_b32_e64 v174, v202, v174, s[42:43]
	v_cndmask_b32_e64 v213, v213, 1.0, s[42:43]
	v_mul_f32_e32 v214, 0xbe0293ee, v174
	s_nop 0
	v_cmp_gt_f32_e32 vcc, 1.0, v213
	v_fma_f32 v80, v80, s92, v214
	v_fma_f32 v81, v81, s92, v214
	v_fma_f32 v82, v82, s92, v214
	v_fma_f32 v83, v83, s92, v214
	v_fma_f32 v84, v84, s92, v214
	v_fma_f32 v85, v85, s92, v214
	v_fma_f32 v86, v86, s92, v214
	v_fma_f32 v87, v87, s92, v214
	v_fma_f32 v88, v88, s92, v214
	v_fma_f32 v89, v89, s92, v214
	v_fma_f32 v90, v90, s92, v214
	v_fma_f32 v91, v91, s92, v214
	v_fma_f32 v92, v92, s92, v214
	v_fma_f32 v93, v93, s92, v214
	v_fma_f32 v94, v94, s92, v214
	v_fma_f32 v95, v95, s92, v214
	v_fma_f32 v64, v64, s92, v214
	v_fma_f32 v65, v65, s92, v214
	v_fma_f32 v66, v66, s92, v214
	v_fma_f32 v67, v67, s92, v214
	v_fma_f32 v68, v68, s92, v214
	v_fma_f32 v69, v69, s92, v214
	v_fma_f32 v70, v70, s92, v214
	v_fma_f32 v71, v71, s92, v214
	v_fma_f32 v72, v72, s92, v214
	v_fma_f32 v73, v73, s92, v214
	v_fma_f32 v74, v74, s92, v214
	v_fma_f32 v75, v75, s92, v214
	v_fma_f32 v76, v76, s92, v214
	v_fma_f32 v77, v77, s92, v214
	v_fma_f32 v78, v78, s92, v214
	v_fma_f32 v79, v79, s92, v214
	s_cbranch_vccz .Lda_noresc_2
	s_and_saveexec_b64 s[34:35], s[40:41]
	ds_write_b32 v199, v213 offset:128
	s_or_b64 exec, exec, s[34:35]
	s_waitcnt lgkmcnt(0)
	v_add_u32_e32 v215, v99, v96
	ds_read_b128 v[228:231], v215 offset:128
	ds_read_b128 v[232:235], v215 offset:160
	ds_read_b128 v[236:239], v215 offset:192
	ds_read_b128 v[240:243], v215 offset:224
	s_waitcnt lgkmcnt(0)
	v_pk_mul_f32 v[0:1], v[0:1], v[228:229]
	v_pk_mul_f32 v[2:3], v[2:3], v[230:231]
	v_pk_mul_f32 v[4:5], v[4:5], v[232:233]
	v_pk_mul_f32 v[6:7], v[6:7], v[234:235]
	v_pk_mul_f32 v[8:9], v[8:9], v[236:237]
	v_pk_mul_f32 v[10:11], v[10:11], v[238:239]
	v_pk_mul_f32 v[12:13], v[12:13], v[240:241]
	v_pk_mul_f32 v[14:15], v[14:15], v[242:243]
	v_pk_mul_f32 v[48:49], v[48:49], v[228:229]
	v_pk_mul_f32 v[50:51], v[50:51], v[230:231]
	v_pk_mul_f32 v[52:53], v[52:53], v[232:233]
	v_pk_mul_f32 v[54:55], v[54:55], v[234:235]
	v_pk_mul_f32 v[56:57], v[56:57], v[236:237]
	v_pk_mul_f32 v[58:59], v[58:59], v[238:239]
	v_pk_mul_f32 v[60:61], v[60:61], v[240:241]
	v_pk_mul_f32 v[62:63], v[62:63], v[242:243]
	v_pk_mul_f32 v[32:33], v[32:33], v[228:229]
	v_pk_mul_f32 v[34:35], v[34:35], v[230:231]
	v_pk_mul_f32 v[36:37], v[36:37], v[232:233]
	v_pk_mul_f32 v[38:39], v[38:39], v[234:235]
	v_pk_mul_f32 v[40:41], v[40:41], v[236:237]
	v_pk_mul_f32 v[42:43], v[42:43], v[238:239]
	v_pk_mul_f32 v[44:45], v[44:45], v[240:241]
	v_pk_mul_f32 v[46:47], v[46:47], v[242:243]
	v_pk_mul_f32 v[16:17], v[16:17], v[228:229]
	v_pk_mul_f32 v[18:19], v[18:19], v[230:231]
	v_pk_mul_f32 v[20:21], v[20:21], v[232:233]
	v_pk_mul_f32 v[22:23], v[22:23], v[234:235]
	v_pk_mul_f32 v[24:25], v[24:25], v[236:237]
	v_pk_mul_f32 v[26:27], v[26:27], v[238:239]
	v_pk_mul_f32 v[28:29], v[28:29], v[240:241]
	v_pk_mul_f32 v[30:31], v[30:31], v[242:243]
.Lda_noresc_2:
	v_exp_f32_e32 v80, v80
	v_exp_f32_e32 v81, v81
	v_exp_f32_e32 v82, v82
	v_exp_f32_e32 v83, v83
	v_exp_f32_e32 v84, v84
	v_exp_f32_e32 v85, v85
	v_exp_f32_e32 v86, v86
	v_exp_f32_e32 v87, v87
	v_exp_f32_e32 v88, v88
	v_exp_f32_e32 v89, v89
	v_exp_f32_e32 v90, v90
	v_exp_f32_e32 v91, v91
	v_exp_f32_e32 v92, v92
	v_exp_f32_e32 v93, v93
	v_exp_f32_e32 v94, v94
	v_exp_f32_e32 v95, v95
	v_exp_f32_e32 v64, v64
	v_exp_f32_e32 v65, v65
	v_exp_f32_e32 v66, v66
	v_exp_f32_e32 v67, v67
	v_exp_f32_e32 v68, v68
	v_exp_f32_e32 v69, v69
	v_exp_f32_e32 v70, v70
	v_exp_f32_e32 v71, v71
	v_exp_f32_e32 v72, v72
	v_exp_f32_e32 v73, v73
	v_exp_f32_e32 v74, v74
	v_exp_f32_e32 v75, v75
	v_exp_f32_e32 v76, v76
	v_exp_f32_e32 v77, v77
	v_exp_f32_e32 v78, v78
	v_exp_f32_e32 v79, v79
	v_add_f32_e32 v201, v80, v81
	v_add_f32_e32 v202, v82, v83
	v_add_f32_e32 v201, v201, v84
	v_add_f32_e32 v202, v202, v85
	v_add_f32_e32 v201, v201, v86
	v_add_f32_e32 v202, v202, v87
	v_add_f32_e32 v201, v201, v88
	v_add_f32_e32 v202, v202, v89
	v_add_f32_e32 v201, v201, v90
	v_add_f32_e32 v202, v202, v91
	v_add_f32_e32 v201, v201, v92
	v_add_f32_e32 v202, v202, v93
	v_add_f32_e32 v201, v201, v94
	v_add_f32_e32 v202, v202, v95
	v_add_f32_e32 v201, v201, v64
	v_add_f32_e32 v202, v202, v65
	v_add_f32_e32 v201, v201, v66
	v_add_f32_e32 v202, v202, v67
	v_add_f32_e32 v201, v201, v68
	v_add_f32_e32 v202, v202, v69
	v_add_f32_e32 v201, v201, v70
	v_add_f32_e32 v202, v202, v71
	v_add_f32_e32 v201, v201, v72
	v_add_f32_e32 v202, v202, v73
	v_add_f32_e32 v201, v201, v74
	v_add_f32_e32 v202, v202, v75
	v_add_f32_e32 v201, v201, v76
	v_add_f32_e32 v202, v202, v77
	v_add_f32_e32 v201, v201, v78
	v_add_f32_e32 v202, v202, v79
	v_add_f32_e32 v201, v201, v202
	v_mov_b32_e32 v202, v201
	v_cvt_pk_bf16_f32 v166, v80, v81
	v_cvt_pk_bf16_f32 v167, v82, v83
	v_cvt_pk_bf16_f32 v168, v84, v85
	v_cvt_pk_bf16_f32 v169, v86, v87
	v_cvt_pk_bf16_f32 v170, v88, v89
	v_cvt_pk_bf16_f32 v171, v90, v91
	v_cvt_pk_bf16_f32 v172, v92, v93
	v_cvt_pk_bf16_f32 v173, v94, v95
	v_cvt_pk_bf16_f32 v176, v64, v65
	v_cvt_pk_bf16_f32 v177, v66, v67
	v_cvt_pk_bf16_f32 v178, v68, v69
	v_cvt_pk_bf16_f32 v179, v70, v71
	v_cvt_pk_bf16_f32 v180, v72, v73
	v_cvt_pk_bf16_f32 v181, v74, v75
	v_cvt_pk_bf16_f32 v182, v76, v77
	v_cvt_pk_bf16_f32 v183, v78, v79
	s_nop 1
	v_permlane32_swap_b32_e32 v201, v202
	v_permlane32_swap_b32_e32 v166, v168
	v_permlane32_swap_b32_e32 v167, v169
	v_permlane32_swap_b32_e32 v170, v172
	v_permlane32_swap_b32_e32 v171, v173
	v_permlane32_swap_b32_e32 v176, v178
	v_permlane32_swap_b32_e32 v177, v179
	v_permlane32_swap_b32_e32 v180, v182
	v_permlane32_swap_b32_e32 v181, v183
	v_add_f32_e32 v201, v201, v202
	v_fma_f32 v175, v175, v213, v201
	s_cmp_lt_u32 s100, 130
	s_cbranch_scc0 .Lda_skipw_2
	s_waitcnt vmcnt(0)
	ds_write_b128 v197, v[134:137] offset:0
	ds_write_b128 v197, v[138:141] offset:8192
	ds_write_b128 v200, v[142:145] offset:0
	ds_write_b128 v200, v[146:149] offset:8192
	s_nop 1

; #define SBAR() __builtin_amdgcn_sched_barrier(0)
; __device__ __forceinline__ void qkt(f32x16& p0, f32x16& p1, const bf16_t* Ks, const bf16x8* qr, int r32, int hi) {
;   p0 = f32x16{}; p1 = f32x16{};
; #pragma unroll
;   for (int d0 = 0; d0 < 8; ++d0) { int cb = (d0 * 16 + hi * 8) * 2;
;     bf16x8 b0 = *reinterpret_cast<const bf16x8*>((const char*)Ks + KSWZ(r32, cb));
;     bf16x8 b1 = *reinterpret_cast<const bf16x8*>((const char*)Ks + KSWZ(32 + r32, cb));
;     p0 = __builtin_amdgcn_mfma_f32_32x32x16_bf16(b0, qr[d0], p0, 0, 0, 0);
;     p1 = __builtin_amdgcn_mfma_f32_32x32x16_bf16(b1, qr[d0], p1, 0, 0, 0); }
; }
; __device__ __forceinline__ int v_st(int k, int c) { const int kk = (k & ~0xC) | ((k & 4) << 1) | ((k & 8) >> 1); return ((kk >> 3) * 4 + (c >> 5)) * 512 + ((kk & 7) * 32 + (c & 31)) * 2; }
; __device__ __forceinline__ int v_rd_base(int lane) { return ((lane & 3) << 3) | (((lane >> 2) & 3) << 6) | (((lane >> 4) & 1) << 5) | (((lane >> 5) & 1) << 8); }
; template <int OFF> __device__ __forceinline__ s16x4 tr_read(int vb) {
;   s16x4 r; asm volatile("ds_read_b64_tr_b16 %0, %1 offset:%2" : "=&v"(r) : "v"(vb), "i"(OFF) : "memory"); return r;
; }
; template <int D0> __device__ __forceinline__ void pv_one(f32x16& od, int vb, bf16x8 pa0, bf16x8 pa1, bf16x8 pa2, bf16x8 pa3) {
;   const s16x4 l0 = tr_read<v_rd_off(D0, 0, 0)>(vb), h0 = tr_read<v_rd_off(D0, 0, 1)>(vb), l1 = tr_read<v_rd_off(D0, 1, 0)>(vb), h1 = tr_read<v_rd_off(D0, 1, 1)>(vb);
;   const s16x4 l2 = tr_read<v_rd_off(D0, 2, 0)>(vb), h2 = tr_read<v_rd_off(D0, 2, 1)>(vb), l3 = tr_read<v_rd_off(D0, 3, 0)>(vb), h3 = tr_read<v_rd_off(D0, 3, 1)>(vb);
;   asm volatile("s_waitcnt lgkmcnt(0)" ::: "memory"); SBAR();
;     ...
;   od = __builtin_amdgcn_mfma_f32_32x32x16_bf16(pa0, PK(l0, h0), od, 0, 0, 0);
;   od = __builtin_amdgcn_mfma_f32_32x32x16_bf16(pa1, PK(l1, h1), od, 0, 0, 0);
;   od = __builtin_amdgcn_mfma_f32_32x32x16_bf16(pa2, PK(l2, h2), od, 0, 0, 0);
;   od = __builtin_amdgcn_mfma_f32_32x32x16_bf16(pa3, PK(l3, h3), od, 0, 0, 0);
;     ...
; }
; __device__ __forceinline__ void pv_d0(f32x16* o, int vb, bf16x8 pa0, bf16x8 pa1, bf16x8 pa2, bf16x8 pa3) {
;   pv_one<0>(o[0], vb, pa0, pa1, pa2, pa3); pv_one<1>(o[1], vb, pa0, pa1, pa2, pa3); pv_one<2>(o[2], vb, pa0, pa1, pa2, pa3); pv_one<3>(o[3], vb, pa0, pa1, pa2, pa3);
.Lda_skipl_2:
	s_add_u32 s100, s100, 1
	s_cmp_lt_u32 s100, 132
	s_cbranch_scc0 .Lda_skipk_2
	ds_read_b128 v[150:153], v204 offset:49152
	ds_read_b128 v[154:157], v204 offset:57344
	ds_read_b128 v[158:161], v205 offset:49152
	ds_read_b128 v[162:165], v205 offset:57344
	ds_read_b128 v[228:231], v206 offset:49152
	ds_read_b128 v[232:235], v206 offset:57344
	ds_read_b128 v[236:239], v207 offset:49152
	ds_read_b128 v[240:243], v207 offset:57344
.Lda_skipk_2:
	s_barrier
	s_waitcnt lgkmcnt(6)
	v_mfma_f32_32x32x16_bf16 v[80:95], v[150:153], v[130:133], 0
	v_mfma_f32_32x32x16_bf16 v[64:79], v[154:157], v[130:133], 0
	ds_read_b128 v[150:153], v208 offset:49152
	ds_read_b128 v[154:157], v208 offset:57344
	s_waitcnt lgkmcnt(6)
	v_mfma_f32_32x32x16_bf16 v[80:95], v[158:161], v[126:129], v[80:95]
	v_mfma_f32_32x32x16_bf16 v[64:79], v[162:165], v[126:129], v[64:79]
	ds_read_b128 v[158:161], v209 offset:49152
	ds_read_b128 v[162:165], v209 offset:57344
	s_waitcnt lgkmcnt(6)
	v_mfma_f32_32x32x16_bf16 v[80:95], v[228:231], v[122:125], v[80:95]
	v_mfma_f32_32x32x16_bf16 v[64:79], v[232:235], v[122:125], v[64:79]
	ds_read_b128 v[228:231], v210 offset:49152
	ds_read_b128 v[232:235], v210 offset:57344
	s_waitcnt lgkmcnt(6)
	v_mfma_f32_32x32x16_bf16 v[80:95], v[236:239], v[118:121], v[80:95]
	v_mfma_f32_32x32x16_bf16 v[64:79], v[240:243], v[118:121], v[64:79]
	ds_read_b128 v[236:239], v211 offset:49152
	ds_read_b128 v[240:243], v211 offset:57344
	s_waitcnt lgkmcnt(6)
	v_mfma_f32_32x32x16_bf16 v[80:95], v[150:153], v[114:117], v[80:95]
	v_mfma_f32_32x32x16_bf16 v[64:79], v[154:157], v[114:117], v[64:79]
	ds_read_b64_tr_b16 v[150:151], v196 offset:32768
	ds_read_b64_tr_b16 v[152:153], v196 offset:34816
	ds_read_b64_tr_b16 v[154:155], v196 offset:36864
	ds_read_b64_tr_b16 v[156:157], v196 offset:38912
	s_waitcnt lgkmcnt(8)
	v_mfma_f32_32x32x16_bf16 v[80:95], v[158:161], v[110:113], v[80:95]
	v_mfma_f32_32x32x16_bf16 v[64:79], v[162:165], v[110:113], v[64:79]
	ds_read_b64_tr_b16 v[158:159], v196 offset:40960
	ds_read_b64_tr_b16 v[160:161], v196 offset:43008
	ds_read_b64_tr_b16 v[162:163], v196 offset:45056
	ds_read_b64_tr_b16 v[164:165], v196 offset:47104
	s_waitcnt lgkmcnt(10)
	v_mfma_f32_32x32x16_bf16 v[80:95], v[228:231], v[106:109], v[80:95]
	v_mfma_f32_32x32x16_bf16 v[64:79], v[232:235], v[106:109], v[64:79]
	ds_read_b64_tr_b16 v[228:229], v196 offset:33280
	ds_read_b64_tr_b16 v[230:231], v196 offset:35328
	ds_read_b64_tr_b16 v[232:233], v196 offset:37376
	ds_read_b64_tr_b16 v[234:235], v196 offset:39424
	s_waitcnt lgkmcnt(12)
	v_mfma_f32_32x32x16_bf16 v[80:95], v[236:239], v[102:105], v[80:95]
	v_mfma_f32_32x32x16_bf16 v[64:79], v[240:243], v[102:105], v[64:79]
	ds_read_b64_tr_b16 v[236:237], v196 offset:41472
	ds_read_b64_tr_b16 v[238:239], v196 offset:43520
	s_waitcnt lgkmcnt(12)
	v_mfma_f32_32x32x16_bf16 v[0:15], v[166:169], v[150:153], v[0:15]
	ds_read_b64_tr_b16 v[240:241], v196 offset:45568
	ds_read_b64_tr_b16 v[242:243], v196 offset:47616
	s_waitcnt lgkmcnt(12)
	v_mfma_f32_32x32x16_bf16 v[0:15], v[170:173], v[154:157], v[0:15]
	ds_read_b64_tr_b16 v[150:151], v196 offset:33792
	ds_read_b64_tr_b16 v[152:153], v196 offset:35840
	s_waitcnt lgkmcnt(12)
	v_mfma_f32_32x32x16_bf16 v[0:15], v[176:179], v[158:161], v[0:15]
	ds_read_b64_tr_b16 v[154:155], v196 offset:37888
	ds_read_b64_tr_b16 v[156:157], v196 offset:39936
	s_waitcnt lgkmcnt(12)
	v_mfma_f32_32x32x16_bf16 v[0:15], v[180:183], v[162:165], v[0:15]
	ds_read_b64_tr_b16 v[158:159], v196 offset:41984
	ds_read_b64_tr_b16 v[160:161], v196 offset:44032
	s_waitcnt lgkmcnt(12)
	v_mfma_f32_32x32x16_bf16 v[48:63], v[166:169], v[228:231], v[48:63]
	ds_read_b64_tr_b16 v[162:163], v196 offset:46080
	ds_read_b64_tr_b16 v[164:165], v196 offset:48128
	s_waitcnt lgkmcnt(12)
	v_mfma_f32_32x32x16_bf16 v[48:63], v[170:173], v[232:235], v[48:63]
	ds_read_b64_tr_b16 v[228:229], v196 offset:34304
	ds_read_b64_tr_b16 v[230:231], v196 offset:36352
	s_waitcnt lgkmcnt(12)
	v_mfma_f32_32x32x16_bf16 v[48:63], v[176:179], v[236:239], v[48:63]
	ds_read_b64_tr_b16 v[232:233], v196 offset:38400
	ds_read_b64_tr_b16 v[234:235], v196 offset:40448
	s_waitcnt lgkmcnt(12)
	v_mfma_f32_32x32x16_bf16 v[48:63], v[180:183], v[240:243], v[48:63]
	ds_read_b64_tr_b16 v[236:237], v196 offset:42496
	ds_read_b64_tr_b16 v[238:239], v196 offset:44544
	s_waitcnt lgkmcnt(12)
	v_mfma_f32_32x32x16_bf16 v[32:47], v[166:169], v[150:153], v[32:47]
	ds_read_b64_tr_b16 v[240:241], v196 offset:46592
	ds_read_b64_tr_b16 v[242:243], v196 offset:48640
	s_waitcnt lgkmcnt(12)
	v_mfma_f32_32x32x16_bf16 v[32:47], v[170:173], v[154:157], v[32:47]
	s_waitcnt lgkmcnt(10)
	v_mfma_f32_32x32x16_bf16 v[32:47], v[176:179], v[158:161], v[32:47]
	s_waitcnt lgkmcnt(8)
	v_mfma_f32_32x32x16_bf16 v[32:47], v[180:183], v[162:165], v[32:47]
	s_waitcnt lgkmcnt(6)
	v_mfma_f32_32x32x16_bf16 v[16:31], v[166:169], v[228:231], v[16:31]
	s_waitcnt lgkmcnt(4)
	v_mfma_f32_32x32x16_bf16 v[16:31], v[170:173], v[232:235], v[16:31]
	s_waitcnt lgkmcnt(2)
	v_mfma_f32_32x32x16_bf16 v[16:31], v[176:179], v[236:239], v[16:31]
	s_waitcnt lgkmcnt(0)
	v_mfma_f32_32x32x16_bf16 v[16:31], v[180:183], v[240:243], v[16:31]
	s_barrier
; __device__ __forceinline__ void partialSM(f32x16& p0, f32x16& p1, float& m_reg, float& mn, float& alpha) {
;   constexpr float C = SCALE * 1.4426950408889634f;
;   float pmax = p0[0];
; #pragma unroll
;   for (int r = 1; r < 16; ++r) pmax = fmaxf(pmax, p0[r]);
; #pragma unroll
;   for (int r = 0; r < 16; ++r) pmax = fmaxf(pmax, p1[r]);
;   { auto rr = __builtin_amdgcn_permlane32_swap(__float_as_uint(pmax), __float_as_uint(pmax), false, false);
;     pmax = fmaxf(__uint_as_float(rr[0]), __uint_as_float(rr[1])); }
;   if (__builtin_expect(__all(pmax - m_reg <= THR / SCALE), 1)) { mn = m_reg; alpha = 1.f; }
;   else { mn = fmaxf(m_reg, pmax); alpha = __builtin_amdgcn_exp2f((m_reg - mn) * C); m_reg = mn; }
;   float mnC = -mn * C;
; #pragma unroll
;   for (int r = 0; r < 16; ++r) p0[r] = fmaf(p0[r], C, mnC);
; #pragma unroll
;   for (int r = 0; r < 16; ++r) p1[r] = fmaf(p1[r], C, mnC);
; #pragma unroll
;   for (int r = 0; r < 16; ++r) p0[r] = __builtin_amdgcn_exp2f(p0[r]);
; }
; __device__ __forceinline__ void finishSM(f32x16& p0, f32x16& p1, float alpha, float& l_reg, bf16x8& pa0, bf16x8& pa1, bf16x8& pa2, bf16x8& pa3) {
; #pragma unroll
;   for (int r = 0; r < 16; ++r) p1[r] = __builtin_amdgcn_exp2f(p1[r]);
;   float ps = 0;
; #pragma unroll
;   for (int r = 0; r < 16; ++r) ps += p0[r];
; #pragma unroll
;   for (int r = 0; r < 16; ++r) ps += p1[r];
;   { auto rr = __builtin_amdgcn_permlane32_swap(__float_as_uint(ps), __float_as_uint(ps), false, false);
;     ps = __uint_as_float(rr[0]) + __uint_as_float(rr[1]); }
;   l_reg = l_reg * alpha + ps;
;     ...
;   PK4(p0, 0, pa0); PK4(p0, 8, pa1); PK4(p1, 0, pa2); PK4(p1, 8, pa3);
;     ...
; }
	v_max3_f32 v201, v80, v81, v82
	v_max3_f32 v202, v64, v65, v66
	v_max3_f32 v201, v201, v83, v84
	v_max3_f32 v202, v202, v67, v68
	v_max3_f32 v201, v201, v85, v86
	v_max3_f32 v202, v202, v69, v70
	v_max3_f32 v201, v201, v87, v88
	v_max3_f32 v202, v202, v71, v72
	v_max3_f32 v201, v201, v89, v90
	v_max3_f32 v202, v202, v73, v74
	v_max3_f32 v201, v201, v91, v92
	v_max3_f32 v202, v202, v75, v76
	v_max3_f32 v201, v201, v93, v94
	v_max3_f32 v202, v202, v77, v78
	v_max3_f32 v201, v201, v95, v79
	v_max_f32_e32 v201, v201, v202
	v_mov_b32_e32 v202, v201
	s_nop 1
	v_permlane32_swap_b32_e32 v201, v202
	s_nop 0
	v_max_f32_e32 v212, v201, v202
	v_sub_f32_e32 v201, v212, v174
	v_cmp_ge_f32_e32 vcc, s86, v201
	v_max_f32_e32 v202, v174, v212
	v_sub_f32_e32 v215, v174, v202
	v_mul_f32_e32 v215, s92, v215
	s_nop 1
	s_cmp_eq_u64 vcc, exec
	s_cselect_b64 s[42:43], -1, 0
	v_exp_f32_e32 v213, v215
	s_nop 0
	v_cndmask_b32_e64 v174, v202, v174, s[42:43]
	v_cndmask_b32_e64 v213, v213, 1.0, s[42:43]
	v_mul_f32_e32 v214, 0xbe0293ee, v174
	s_nop 0
	v_cmp_gt_f32_e32 vcc, 1.0, v213
	v_fma_f32 v80, v80, s92, v214
	v_fma_f32 v81, v81, s92, v214
	v_fma_f32 v82, v82, s92, v214
	v_fma_f32 v83, v83, s92, v214
	v_fma_f32 v84, v84, s92, v214
	v_fma_f32 v85, v85, s92, v214
	v_fma_f32 v86, v86, s92, v214
	v_fma_f32 v87, v87, s92, v214
	v_fma_f32 v88, v88, s92, v214
	v_fma_f32 v89, v89, s92, v214
	v_fma_f32 v90, v90, s92, v214
	v_fma_f32 v91, v91, s92, v214
	v_fma_f32 v92, v92, s92, v214
	v_fma_f32 v93, v93, s92, v214
	v_fma_f32 v94, v94, s92, v214
	v_fma_f32 v95, v95, s92, v214
	v_fma_f32 v64, v64, s92, v214
	v_fma_f32 v65, v65, s92, v214
	v_fma_f32 v66, v66, s92, v214
	v_fma_f32 v67, v67, s92, v214
	v_fma_f32 v68, v68, s92, v214
	v_fma_f32 v69, v69, s92, v214
	v_fma_f32 v70, v70, s92, v214
	v_fma_f32 v71, v71, s92, v214
	v_fma_f32 v72, v72, s92, v214
	v_fma_f32 v73, v73, s92, v214
	v_fma_f32 v74, v74, s92, v214
	v_fma_f32 v75, v75, s92, v214
	v_fma_f32 v76, v76, s92, v214
	v_fma_f32 v77, v77, s92, v214
	v_fma_f32 v78, v78, s92, v214
	v_fma_f32 v79, v79, s92, v214
	s_cbranch_vccz .Lda_noresc_3
	s_and_saveexec_b64 s[34:35], s[40:41]
	ds_write_b32 v199, v213 offset:128
	s_or_b64 exec, exec, s[34:35]
	s_waitcnt lgkmcnt(0)
	v_add_u32_e32 v215, v99, v96
	ds_read_b128 v[228:231], v215 offset:128
	ds_read_b128 v[232:235], v215 offset:160
	ds_read_b128 v[236:239], v215 offset:192
	ds_read_b128 v[240:243], v215 offset:224
	s_waitcnt lgkmcnt(0)
	v_pk_mul_f32 v[0:1], v[0:1], v[228:229]
	v_pk_mul_f32 v[2:3], v[2:3], v[230:231]
	v_pk_mul_f32 v[4:5], v[4:5], v[232:233]
	v_pk_mul_f32 v[6:7], v[6:7], v[234:235]
	v_pk_mul_f32 v[8:9], v[8:9], v[236:237]
	v_pk_mul_f32 v[10:11], v[10:11], v[238:239]
	v_pk_mul_f32 v[12:13], v[12:13], v[240:241]
	v_pk_mul_f32 v[14:15], v[14:15], v[242:243]
	v_pk_mul_f32 v[48:49], v[48:49], v[228:229]
	v_pk_mul_f32 v[50:51], v[50:51], v[230:231]
	v_pk_mul_f32 v[52:53], v[52:53], v[232:233]
	v_pk_mul_f32 v[54:55], v[54:55], v[234:235]
	v_pk_mul_f32 v[56:57], v[56:57], v[236:237]
	v_pk_mul_f32 v[58:59], v[58:59], v[238:239]
	v_pk_mul_f32 v[60:61], v[60:61], v[240:241]
	v_pk_mul_f32 v[62:63], v[62:63], v[242:243]
	v_pk_mul_f32 v[32:33], v[32:33], v[228:229]
	v_pk_mul_f32 v[34:35], v[34:35], v[230:231]
	v_pk_mul_f32 v[36:37], v[36:37], v[232:233]
	v_pk_mul_f32 v[38:39], v[38:39], v[234:235]
	v_pk_mul_f32 v[40:41], v[40:41], v[236:237]
	v_pk_mul_f32 v[42:43], v[42:43], v[238:239]
	v_pk_mul_f32 v[44:45], v[44:45], v[240:241]
	v_pk_mul_f32 v[46:47], v[46:47], v[242:243]
	v_pk_mul_f32 v[16:17], v[16:17], v[228:229]
	v_pk_mul_f32 v[18:19], v[18:19], v[230:231]
	v_pk_mul_f32 v[20:21], v[20:21], v[232:233]
	v_pk_mul_f32 v[22:23], v[22:23], v[234:235]
	v_pk_mul_f32 v[24:25], v[24:25], v[236:237]
	v_pk_mul_f32 v[26:27], v[26:27], v[238:239]
	v_pk_mul_f32 v[28:29], v[28:29], v[240:241]
	v_pk_mul_f32 v[30:31], v[30:31], v[242:243]
.Lda_noresc_3:
	v_exp_f32_e32 v80, v80
	v_exp_f32_e32 v81, v81
	v_exp_f32_e32 v82, v82
	v_exp_f32_e32 v83, v83
	v_exp_f32_e32 v84, v84
	v_exp_f32_e32 v85, v85
	v_exp_f32_e32 v86, v86
	v_exp_f32_e32 v87, v87
	v_exp_f32_e32 v88, v88
	v_exp_f32_e32 v89, v89
	v_exp_f32_e32 v90, v90
	v_exp_f32_e32 v91, v91
	v_exp_f32_e32 v92, v92
	v_exp_f32_e32 v93, v93
	v_exp_f32_e32 v94, v94
	v_exp_f32_e32 v95, v95
	v_exp_f32_e32 v64, v64
	v_exp_f32_e32 v65, v65
	v_exp_f32_e32 v66, v66
	v_exp_f32_e32 v67, v67
	v_exp_f32_e32 v68, v68
	v_exp_f32_e32 v69, v69
	v_exp_f32_e32 v70, v70
	v_exp_f32_e32 v71, v71
	v_exp_f32_e32 v72, v72
	v_exp_f32_e32 v73, v73
	v_exp_f32_e32 v74, v74
	v_exp_f32_e32 v75, v75
	v_exp_f32_e32 v76, v76
	v_exp_f32_e32 v77, v77
	v_exp_f32_e32 v78, v78
	v_exp_f32_e32 v79, v79
	v_add_f32_e32 v201, v80, v81
	v_add_f32_e32 v202, v82, v83
	v_add_f32_e32 v201, v201, v84
	v_add_f32_e32 v202, v202, v85
	v_add_f32_e32 v201, v201, v86
	v_add_f32_e32 v202, v202, v87
	v_add_f32_e32 v201, v201, v88
	v_add_f32_e32 v202, v202, v89
	v_add_f32_e32 v201, v201, v90
	v_add_f32_e32 v202, v202, v91
	v_add_f32_e32 v201, v201, v92
	v_add_f32_e32 v202, v202, v93
	v_add_f32_e32 v201, v201, v94
	v_add_f32_e32 v202, v202, v95
	v_add_f32_e32 v201, v201, v64
	v_add_f32_e32 v202, v202, v65
	v_add_f32_e32 v201, v201, v66
	v_add_f32_e32 v202, v202, v67
	v_add_f32_e32 v201, v201, v68
	v_add_f32_e32 v202, v202, v69
	v_add_f32_e32 v201, v201, v70
	v_add_f32_e32 v202, v202, v71
	v_add_f32_e32 v201, v201, v72
	v_add_f32_e32 v202, v202, v73
	v_add_f32_e32 v201, v201, v74
	v_add_f32_e32 v202, v202, v75
	v_add_f32_e32 v201, v201, v76
	v_add_f32_e32 v202, v202, v77
	v_add_f32_e32 v201, v201, v78
	v_add_f32_e32 v202, v202, v79
	v_add_f32_e32 v201, v201, v202
	v_mov_b32_e32 v202, v201
	v_cvt_pk_bf16_f32 v166, v80, v81
	v_cvt_pk_bf16_f32 v167, v82, v83
	v_cvt_pk_bf16_f32 v168, v84, v85
	v_cvt_pk_bf16_f32 v169, v86, v87
	v_cvt_pk_bf16_f32 v170, v88, v89
	v_cvt_pk_bf16_f32 v171, v90, v91
	v_cvt_pk_bf16_f32 v172, v92, v93
	v_cvt_pk_bf16_f32 v173, v94, v95
	v_cvt_pk_bf16_f32 v176, v64, v65
	v_cvt_pk_bf16_f32 v177, v66, v67
	v_cvt_pk_bf16_f32 v178, v68, v69
	v_cvt_pk_bf16_f32 v179, v70, v71
	v_cvt_pk_bf16_f32 v180, v72, v73
	v_cvt_pk_bf16_f32 v181, v74, v75
	v_cvt_pk_bf16_f32 v182, v76, v77
	v_cvt_pk_bf16_f32 v183, v78, v79
	s_nop 1
	v_permlane32_swap_b32_e32 v201, v202
	v_permlane32_swap_b32_e32 v166, v168
	v_permlane32_swap_b32_e32 v167, v169
	v_permlane32_swap_b32_e32 v170, v172
	v_permlane32_swap_b32_e32 v171, v173
	v_permlane32_swap_b32_e32 v176, v178
	v_permlane32_swap_b32_e32 v177, v179
	v_permlane32_swap_b32_e32 v180, v182
	v_permlane32_swap_b32_e32 v181, v183
	v_add_f32_e32 v201, v201, v202
	v_fma_f32 v175, v175, v213, v201
	s_cmp_lt_u32 s100, 130
	s_cbranch_scc0 .Lda_skipw_3
	s_waitcnt vmcnt(0)
	ds_write_b128 v197, v[134:137] offset:16384
	ds_write_b128 v197, v[138:141] offset:24576
	ds_write_b128 v200, v[142:145] offset:16384
	ds_write_b128 v200, v[146:149] offset:24576
	s_nop 1

; #define SBAR() __builtin_amdgcn_sched_barrier(0)
; #define RESC(a) do { if (__any((a) < 1.f)) { if (hi == 0) al_l[r32] = (a); asm volatile("s_waitcnt lgkmcnt(0)" ::: "memory"); \
;     _Pragma("unroll") for (int d = 0; d < 4; ++d) _Pragma("unroll") for (int r = 0; r < 16; ++r) o[d][r] *= al_l[crow(r, hi)]; } } while (0)
; template <int D0> __device__ __forceinline__ void pv_one(f32x16& od, int vb, bf16x8 pa0, bf16x8 pa1, bf16x8 pa2, bf16x8 pa3) {
;   const s16x4 l0 = tr_read<v_rd_off(D0, 0, 0)>(vb), h0 = tr_read<v_rd_off(D0, 0, 1)>(vb), l1 = tr_read<v_rd_off(D0, 1, 0)>(vb), h1 = tr_read<v_rd_off(D0, 1, 1)>(vb);
;   const s16x4 l2 = tr_read<v_rd_off(D0, 2, 0)>(vb), h2 = tr_read<v_rd_off(D0, 2, 1)>(vb), l3 = tr_read<v_rd_off(D0, 3, 0)>(vb), h3 = tr_read<v_rd_off(D0, 3, 1)>(vb);
;   asm volatile("s_waitcnt lgkmcnt(0)" ::: "memory"); SBAR();
;     ...
;   od = __builtin_amdgcn_mfma_f32_32x32x16_bf16(pa0, PK(l0, h0), od, 0, 0, 0);
;   od = __builtin_amdgcn_mfma_f32_32x32x16_bf16(pa1, PK(l1, h1), od, 0, 0, 0);
;   od = __builtin_amdgcn_mfma_f32_32x32x16_bf16(pa2, PK(l2, h2), od, 0, 0, 0);
;   od = __builtin_amdgcn_mfma_f32_32x32x16_bf16(pa3, PK(l3, h3), od, 0, 0, 0);
;     ...
; }
; __device__ __forceinline__ void pv_d0(f32x16* o, int vb, bf16x8 pa0, bf16x8 pa1, bf16x8 pa2, bf16x8 pa3) {
;   pv_one<0>(o[0], vb, pa0, pa1, pa2, pa3); pv_one<1>(o[1], vb, pa0, pa1, pa2, pa3); pv_one<2>(o[2], vb, pa0, pa1, pa2, pa3); pv_one<3>(o[3], vb, pa0, pa1, pa2, pa3);
; template <int MODE, int SDEPTH>
; __device__ __forceinline__ void attn_unit(const UnitP& u, char* lds) {
;     ...
;   SBAR(); qkt(pB0, pB1, (bf16_t*)((char*)K_lds + SHM_K), qr, r32, hi);
;   finishSM(pA0, pA1, alA, l_reg, pa0, pa1, pa2, pa3); SBAR();
;   pv_d0(o, vb0, pa0, pa1, pa2, pa3); mask_tile<MODE>(pB0, pB1, u, NT - 1, wid, r32, hi, biasL); partialSM(pB0, pB1, m_reg, mnB, alB);
;   __syncthreads(); RESC(alB);
;   finishSM(pB0, pB1, alB, l_reg, pa0, pa1, pa2, pa3); SBAR();
;   pv_d0(o, vb0 + (int)SHM_V, pa0, pa1, pa2, pa3);
;   l_reg += __builtin_amdgcn_exp2f(u.sink_l2e - m_reg * (SCALE * 1.4426950408889634f));
;   if (hi == 0) li_l[r32] = l_reg; asm volatile("s_waitcnt lgkmcnt(0)" ::: "memory");
.Lda_skipl_3:
	s_add_u32 s100, s100, 1
	s_cmp_lt_u32 s100, 132
	s_cbranch_scc0 .Lda_skipk_3
	ds_read_b128 v[150:153], v204 offset:0
	ds_read_b128 v[154:157], v204 offset:8192
	ds_read_b128 v[158:161], v205 offset:0
	ds_read_b128 v[162:165], v205 offset:8192
	ds_read_b128 v[228:231], v206 offset:0
	ds_read_b128 v[232:235], v206 offset:8192
	ds_read_b128 v[236:239], v207 offset:0
	ds_read_b128 v[240:243], v207 offset:8192
.Lda_skipk_3:
	s_barrier
	s_cmp_lt_u32 s100, 132
	s_cbranch_scc1 .Lda_loop
	ds_read_b64_tr_b16 v[150:151], v196 offset:49152
	ds_read_b64_tr_b16 v[152:153], v196 offset:51200
	ds_read_b64_tr_b16 v[154:155], v196 offset:53248
	ds_read_b64_tr_b16 v[156:157], v196 offset:55296
	ds_read_b64_tr_b16 v[158:159], v196 offset:57344
	ds_read_b64_tr_b16 v[160:161], v196 offset:59392
	ds_read_b64_tr_b16 v[162:163], v196 offset:61440
	ds_read_b64_tr_b16 v[164:165], v196 offset:63488
	ds_read_b64_tr_b16 v[228:229], v196 offset:49664
	ds_read_b64_tr_b16 v[230:231], v196 offset:51712
	ds_read_b64_tr_b16 v[232:233], v196 offset:53760
	ds_read_b64_tr_b16 v[234:235], v196 offset:55808
	ds_read_b64_tr_b16 v[236:237], v196 offset:57856
	ds_read_b64_tr_b16 v[238:239], v196 offset:59904
	s_waitcnt lgkmcnt(12)
	v_mfma_f32_32x32x16_bf16 v[0:15], v[166:169], v[150:153], v[0:15]
	ds_read_b64_tr_b16 v[240:241], v196 offset:61952
	ds_read_b64_tr_b16 v[242:243], v196 offset:64000
	s_waitcnt lgkmcnt(12)
	v_mfma_f32_32x32x16_bf16 v[0:15], v[170:173], v[154:157], v[0:15]
	ds_read_b64_tr_b16 v[150:151], v196 offset:50176
	ds_read_b64_tr_b16 v[152:153], v196 offset:52224
	s_waitcnt lgkmcnt(12)
	v_mfma_f32_32x32x16_bf16 v[0:15], v[176:179], v[158:161], v[0:15]
	ds_read_b64_tr_b16 v[154:155], v196 offset:54272
	ds_read_b64_tr_b16 v[156:157], v196 offset:56320
	s_waitcnt lgkmcnt(12)
	v_mfma_f32_32x32x16_bf16 v[0:15], v[180:183], v[162:165], v[0:15]
	ds_read_b64_tr_b16 v[158:159], v196 offset:58368
	ds_read_b64_tr_b16 v[160:161], v196 offset:60416
	s_waitcnt lgkmcnt(12)
	v_mfma_f32_32x32x16_bf16 v[48:63], v[166:169], v[228:231], v[48:63]
	ds_read_b64_tr_b16 v[162:163], v196 offset:62464
	ds_read_b64_tr_b16 v[164:165], v196 offset:64512
	s_waitcnt lgkmcnt(12)
	v_mfma_f32_32x32x16_bf16 v[48:63], v[170:173], v[232:235], v[48:63]
	ds_read_b64_tr_b16 v[228:229], v196 offset:50688
	ds_read_b64_tr_b16 v[230:231], v196 offset:52736
	s_waitcnt lgkmcnt(12)
	v_mfma_f32_32x32x16_bf16 v[48:63], v[176:179], v[236:239], v[48:63]
	ds_read_b64_tr_b16 v[232:233], v196 offset:54784
	ds_read_b64_tr_b16 v[234:235], v196 offset:56832
	s_waitcnt lgkmcnt(12)
	v_mfma_f32_32x32x16_bf16 v[48:63], v[180:183], v[240:243], v[48:63]
	ds_read_b64_tr_b16 v[236:237], v196 offset:58880
	ds_read_b64_tr_b16 v[238:239], v196 offset:60928
	s_waitcnt lgkmcnt(12)
	v_mfma_f32_32x32x16_bf16 v[32:47], v[166:169], v[150:153], v[32:47]
	ds_read_b64_tr_b16 v[240:241], v196 offset:62976
	ds_read_b64_tr_b16 v[242:243], v196 offset:65024
	s_waitcnt lgkmcnt(12)
	v_mfma_f32_32x32x16_bf16 v[32:47], v[170:173], v[154:157], v[32:47]
	s_waitcnt lgkmcnt(10)
	v_mfma_f32_32x32x16_bf16 v[32:47], v[176:179], v[158:161], v[32:47]
	s_waitcnt lgkmcnt(8)
	v_mfma_f32_32x32x16_bf16 v[32:47], v[180:183], v[162:165], v[32:47]
	s_waitcnt lgkmcnt(6)
	v_mfma_f32_32x32x16_bf16 v[16:31], v[166:169], v[228:231], v[16:31]
	s_waitcnt lgkmcnt(4)
	v_mfma_f32_32x32x16_bf16 v[16:31], v[170:173], v[232:235], v[16:31]
	s_waitcnt lgkmcnt(2)
	v_mfma_f32_32x32x16_bf16 v[16:31], v[176:179], v[236:239], v[16:31]
	s_waitcnt lgkmcnt(0)
	v_mfma_f32_32x32x16_bf16 v[16:31], v[180:183], v[240:243], v[16:31]
	s_nop 12
	s_cmp_lt_u32 s101, 4
	s_cbranch_scc0 .Lda_trail
	s_barrier
.Lda_trail:
	s_mov_b64 s[34:35], s[84:85]
	v_readlane_b32 s36, v254, 60
	s_and_saveexec_b64 s[10:11], s[40:41]
	ds_write_b32 v199, v175
	s_branch .LBB0_523

; __global__ void __launch_bounds__(512, 2) mk_fwd(Args a) {
	.amdhsa_kernel _Z6mk_fwd4Args
		.amdhsa_group_segment_fixed_size 0
		.amdhsa_private_segment_fixed_size 0
		.amdhsa_kernarg_size 456
		.amdhsa_user_sgpr_count 2
		.amdhsa_user_sgpr_dispatch_ptr 0
		.amdhsa_user_sgpr_queue_ptr 0
		.amdhsa_user_sgpr_kernarg_segment_ptr 1
		.amdhsa_user_sgpr_dispatch_id 0
		.amdhsa_user_sgpr_kernarg_preload_length 0
		.amdhsa_user_sgpr_kernarg_preload_offset 0
		.amdhsa_user_sgpr_private_segment_size 0
		.amdhsa_uses_dynamic_stack 0
		.amdhsa_enable_private_segment 0
		.amdhsa_system_sgpr_workgroup_id_x 1
		.amdhsa_system_sgpr_workgroup_id_y 0
		.amdhsa_system_sgpr_workgroup_id_z 0
		.amdhsa_system_sgpr_workgroup_info 0
		.amdhsa_system_vgpr_workitem_id 2
		.amdhsa_next_free_vgpr 256
		.amdhsa_next_free_sgpr 102
		.amdhsa_accum_offset 256
		.amdhsa_reserve_vcc 1
		.amdhsa_float_round_mode_32 0
		.amdhsa_float_round_mode_16_64 0
		.amdhsa_float_denorm_mode_32 3
		.amdhsa_float_denorm_mode_16_64 3
		.amdhsa_dx10_clamp 1
		.amdhsa_ieee_mode 1
		.amdhsa_fp16_overflow 0
		.amdhsa_tg_split 0
		.amdhsa_exception_fp_ieee_invalid_op 0
		.amdhsa_exception_fp_denorm_src 0
		.amdhsa_exception_fp_ieee_div_zero 0
		.amdhsa_exception_fp_ieee_overflow 0
		.amdhsa_exception_fp_ieee_underflow 0
		.amdhsa_exception_fp_ieee_inexact 0
		.amdhsa_exception_int_div_zero 0
	.end_amdhsa_kernel

; __global__ void __launch_bounds__(512, 2) mk_fwd(Args a) {
.Lfunc_end0:
	.size	_Z6mk_fwd4Args, .Lfunc_end0-_Z6mk_fwd4Args
	.set _Z6mk_fwd4Args.num_vgpr, 256
	.set _Z6mk_fwd4Args.num_agpr, 0
	.set _Z6mk_fwd4Args.numbered_sgpr, 102
	.set _Z6mk_fwd4Args.num_named_barrier, 0
	.set _Z6mk_fwd4Args.private_seg_size, 0
	.set _Z6mk_fwd4Args.uses_vcc, 1
	.set _Z6mk_fwd4Args.uses_flat_scratch, 0
	.set _Z6mk_fwd4Args.has_dyn_sized_stack, 0
	.set _Z6mk_fwd4Args.has_recursion, 0
	.set _Z6mk_fwd4Args.has_indirect_call, 0

; __global__ void __launch_bounds__(512, 2) mk_fwd(Args a) {
amdhsa.kernels:
  - .agpr_count:     0
    .args:
      - .offset:         0
        .size:           200
        .value_kind:     by_value
      - .offset:         200
        .size:           4
        .value_kind:     hidden_block_count_x
      - .offset:         204
        .size:           4
        .value_kind:     hidden_block_count_y
      - .offset:         208
        .size:           4
        .value_kind:     hidden_block_count_z
      - .offset:         212
        .size:           2
        .value_kind:     hidden_group_size_x
      - .offset:         214
        .size:           2
        .value_kind:     hidden_group_size_y
      - .offset:         216
        .size:           2
        .value_kind:     hidden_group_size_z
      - .offset:         218
        .size:           2
        .value_kind:     hidden_remainder_x
      - .offset:         220
        .size:           2
        .value_kind:     hidden_remainder_y
      - .offset:         222
        .size:           2
        .value_kind:     hidden_remainder_z
      - .offset:         240
        .size:           8
        .value_kind:     hidden_global_offset_x
      - .offset:         248
        .size:           8
        .value_kind:     hidden_global_offset_y
      - .offset:         256
        .size:           8
        .value_kind:     hidden_global_offset_z
      - .offset:         264
        .size:           2
        .value_kind:     hidden_grid_dims
      - .offset:         288
        .size:           8
        .value_kind:     hidden_multigrid_sync_arg
      - .offset:         320
        .size:           4
        .value_kind:     hidden_dynamic_lds_size
    .group_segment_fixed_size: 0
    .kernarg_segment_align: 8
    .kernarg_segment_size: 456
    .language:       OpenCL C
    .language_version:
      - 2
      - 0
    .max_flat_workgroup_size: 512
    .name:           _Z6mk_fwd4Args
    .private_segment_fixed_size: 0
    .sgpr_count:     108
    .sgpr_spill_count: 144
    .symbol:         _Z6mk_fwd4Args.kd
    .uniform_work_group_size: 1
    .uses_dynamic_stack: false
    .vgpr_count:     256
    .vgpr_spill_count: 0
    .wavefront_size: 64
